# nt cache hint on once-read streams: x loads (P1 norm, P5 epilogue), G loads (transpose), final f32 output stores
# baseline (speedup 1.0000x reference)
; __device__ __forceinline__ void norm_rows(const float* x, int nrows, const float* g, const float* sc, const float* sh, bf16_t* o, int lane) {
;     ...
;     for (; r0 + 4 <= nrows; r0 += 4) {
;         f32x4 v[4][4];
; #pragma unroll
;         for (int rr = 0; rr < 4; ++rr) { const f32x4* xr = (const f32x4*)(x + (size_t)(r0 + rr) * 1024) + lane;
; #pragma unroll
;             for (int j = 0; j < 4; ++j) v[rr][j] = xr[64 * j]; }
; #pragma unroll
;         for (int rr = 0; rr < 4; ++rr) { float ss = 0.f;
; #pragma unroll
;             for (int j = 0; j < 4; ++j) ss += (v[rr][j].x * v[rr][j].x + v[rr][j].y * v[rr][j].y) + (v[rr][j].z * v[rr][j].z + v[rr][j].w * v[rr][j].w);
;             const float rstd = rsqrtf(wave_sum(ss) * (1.0f / 1024.0f) + 1e-6f);
.LBB0_316:
	v_add_co_u32_e32 v78, vcc, 0xffffd000, v56
	global_load_dwordx4 v[28:31], v[56:57], off offset:-3072 nt
	global_load_dwordx4 v[24:27], v[56:57], off offset:-2048 nt
	global_load_dwordx4 v[20:23], v[56:57], off offset:-1024 nt
	global_load_dwordx4 v[16:19], v[56:57], off nt
	v_addc_co_u32_e32 v79, vcc, -1, v57, vcc
	v_add_co_u32_e32 v114, vcc, 0xffffe000, v56
	global_load_dwordx4 v[86:89], v[78:79], off offset:-3072 nt
	global_load_dwordx4 v[90:93], v[78:79], off offset:-2048 nt
	global_load_dwordx4 v[94:97], v[78:79], off nt
	global_load_dwordx4 v[98:101], v[78:79], off offset:-1024 nt
	v_addc_co_u32_e32 v115, vcc, -1, v57, vcc
	global_load_dwordx4 v[102:105], v[114:115], off offset:-3072 nt
	global_load_dwordx4 v[106:109], v[114:115], off offset:-2048 nt
	global_load_dwordx4 v[110:113], v[114:115], off nt
	s_nop 0
	global_load_dwordx4 v[114:117], v[114:115], off offset:-1024 nt
	v_add_co_u32_e32 v78, vcc, 0xfffff000, v56
	v_mov_b64_e32 v[76:77], s[38:39]
	s_nop 0
	v_addc_co_u32_e32 v79, vcc, -1, v57, vcc
	global_load_dwordx4 v[118:121], v[78:79], off offset:-3072 nt
	global_load_dwordx4 v[122:125], v[78:79], off offset:-2048 nt
	global_load_dwordx4 v[126:129], v[56:57], off offset:-4096 nt
	global_load_dwordx4 v[130:133], v[78:79], off offset:-1024 nt
	v_add_co_u32_e64 v74, s[0:1], s25, v54
	s_add_i32 s47, s47, 4
	s_nop 0
	v_addc_co_u32_e64 v75, s[0:1], -1, v55, s[0:1]
	s_cmp_lt_u32 s47, 32
	v_lshl_add_u64 v[56:57], v[56:57], 0, s[44:45]
	s_waitcnt vmcnt(15)
	v_pk_mul_f32 v[78:79], v[30:31], v[30:31]
	v_pk_mul_f32 v[134:135], v[28:29], v[28:29]
	s_waitcnt vmcnt(14)
	v_pk_mul_f32 v[136:137], v[26:27], v[26:27]
	v_pk_mul_f32 v[138:139], v[24:25], v[24:25]
	s_waitcnt vmcnt(13)
	v_mul_f32_e32 v140, v21, v21
	v_mul_f32_e32 v142, v23, v23
	s_waitcnt vmcnt(12)
	v_mul_f32_e32 v51, v18, v18
	v_mul_f32_e32 v153, v19, v19
	v_pk_mov_b32 v[144:145], v[134:135], v[78:79] op_sel:[1,0]
	v_mov_b32_e32 v135, v79
	v_pk_mov_b32 v[78:79], v[138:139], v[136:137] op_sel:[1,0]
	v_mov_b32_e32 v139, v137
	v_pk_fma_f32 v[136:137], v[20:21], v[20:21], v[140:141] op_sel_hi:[1,1,0]
	v_pk_fma_f32 v[140:141], v[22:23], v[22:23], v[142:143] op_sel_hi:[1,1,0]
	s_waitcnt vmcnt(11)
	v_pk_mul_f32 v[142:143], v[88:89], v[88:89]
	v_pk_mul_f32 v[146:147], v[86:87], v[86:87]
	s_waitcnt vmcnt(10)
	v_pk_mul_f32 v[148:149], v[92:93], v[92:93]
	v_pk_mul_f32 v[150:151], v[90:91], v[90:91]
	s_waitcnt vmcnt(8)
	v_mul_f32_e32 v154, v99, v99
	v_mul_f32_e32 v156, v101, v101
	v_mul_f32_e32 v163, v96, v96
	v_mul_f32_e32 v165, v97, v97
	v_pk_add_f32 v[134:135], v[144:145], v[134:135]
	v_pk_add_f32 v[78:79], v[78:79], v[138:139]
	v_mov_b32_e32 v137, v51
	v_mov_b32_e32 v141, v153
	v_pk_mov_b32 v[138:139], v[146:147], v[142:143] op_sel:[1,0]
	v_mov_b32_e32 v147, v143
	v_pk_mov_b32 v[142:143], v[150:151], v[148:149] op_sel:[1,0]
	v_mov_b32_e32 v151, v149
	v_pk_fma_f32 v[144:145], v[98:99], v[98:99], v[154:155] op_sel_hi:[1,1,0]
	v_pk_fma_f32 v[148:149], v[100:101], v[100:101], v[156:157] op_sel_hi:[1,1,0]
	s_waitcnt vmcnt(7)
	v_pk_mul_f32 v[154:155], v[104:105], v[104:105]
	v_pk_mul_f32 v[156:157], v[102:103], v[102:103]
	s_waitcnt vmcnt(6)
	v_pk_mul_f32 v[158:159], v[108:109], v[108:109]
	v_pk_mul_f32 v[160:161], v[106:107], v[106:107]
	s_waitcnt vmcnt(4)
	v_mul_f32_e32 v162, v115, v115
	v_mul_f32_e32 v164, v117, v117
	v_mul_f32_e32 v37, v16, v16
	v_mul_f32_e32 v39, v17, v17
	v_mul_f32_e32 v172, v112, v112
	v_mul_f32_e32 v173, v113, v113
	v_pk_add_f32 v[134:135], v[134:135], v[134:135] op_sel:[0,1] op_sel_hi:[1,0]
	v_pk_add_f32 v[78:79], v[78:79], v[78:79] op_sel:[0,1] op_sel_hi:[1,0]
	v_pk_add_f32 v[136:137], v[136:137], v[140:141]
	v_pk_add_f32 v[138:139], v[138:139], v[146:147]
	v_pk_add_f32 v[140:141], v[142:143], v[150:151]
	v_mov_b32_e32 v145, v163
	v_mov_b32_e32 v149, v165
	v_pk_mov_b32 v[142:143], v[156:157], v[154:155] op_sel:[1,0]
	v_mov_b32_e32 v157, v155
	v_pk_mov_b32 v[146:147], v[160:161], v[158:159] op_sel:[1,0]
	v_mov_b32_e32 v161, v159
	v_pk_fma_f32 v[150:151], v[114:115], v[114:115], v[162:163] op_sel_hi:[1,1,0]
	v_pk_fma_f32 v[154:155], v[116:117], v[116:117], v[164:165] op_sel_hi:[1,1,0]
	s_waitcnt vmcnt(3)
	v_pk_mul_f32 v[158:159], v[120:121], v[120:121]
	v_pk_mul_f32 v[162:163], v[118:119], v[118:119]
	s_waitcnt vmcnt(2)
	v_pk_mul_f32 v[164:165], v[124:125], v[124:125]
	v_pk_mul_f32 v[166:167], v[122:123], v[122:123]
	v_mul_f32_e32 v169, v94, v94
	v_mul_f32_e32 v171, v95, v95
	v_mov_b32_e32 v135, v37
	v_mov_b32_e32 v79, v39
	v_pk_add_f32 v[138:139], v[138:139], v[138:139] op_sel:[0,1] op_sel_hi:[1,0]
	v_pk_add_f32 v[140:141], v[140:141], v[140:141] op_sel:[0,1] op_sel_hi:[1,0]
	v_pk_add_f32 v[144:145], v[144:145], v[148:149]
	v_pk_add_f32 v[142:143], v[142:143], v[156:157]
	v_pk_add_f32 v[146:147], v[146:147], v[160:161]
	v_mov_b32_e32 v151, v172
	v_mov_b32_e32 v155, v173
	v_pk_mov_b32 v[148:149], v[162:163], v[158:159] op_sel:[1,0]
	v_mov_b32_e32 v163, v159
	v_pk_mov_b32 v[156:157], v[166:167], v[164:165] op_sel:[1,0]
	v_mov_b32_e32 v167, v165
	v_mul_f32_e32 v51, v110, v110
	v_mul_f32_e32 v153, v111, v111
	s_waitcnt vmcnt(0)
; __device__ __forceinline__ unsigned pk2(float lo, float hi) { f32x2 v = {lo, hi}; bf16x2_t b = __builtin_convertvector(v, bf16x2_t); return __builtin_bit_cast(unsigned, b); }
; __device__ __forceinline__ float wave_sum(float v) {
; #pragma unroll
;     for (int o = 1; o < 64; o <<= 1) v += __shfl_xor(v, o);
;     return v;
; }
; __device__ __forceinline__ void norm_rows(const float* x, int nrows, const float* g, const float* sc, const float* sh, bf16_t* o, int lane) {
;     ...
;         for (int rr = 0; rr < 4; ++rr) { float ss = 0.f;
; #pragma unroll
;             for (int j = 0; j < 4; ++j) ss += (v[rr][j].x * v[rr][j].x + v[rr][j].y * v[rr][j].y) + (v[rr][j].z * v[rr][j].z + v[rr][j].w * v[rr][j].w);
;             const float rstd = rsqrtf(wave_sum(ss) * (1.0f / 1024.0f) + 1e-6f);
;             u32x2* op = (u32x2*)(o + (size_t)(r0 + rr) * 1024) + lane;
; #pragma unroll
;             for (int j = 0; j < 4; ++j) { const f32x4 y = v[rr][j] * rstd * gs[j] + shv[j]; u32x2 wv; wv.x = pk2(y.x, y.y); wv.y = pk2(y.z, y.w); op[64 * j] = wv; } }
	v_mul_f32_e32 v168, v131, v131
	v_mul_f32_e32 v170, v133, v133
	v_pk_add_f32 v[78:79], v[134:135], v[78:79]
	v_mov_b32_e32 v139, v169
	v_mov_b32_e32 v141, v171
	v_pk_add_f32 v[134:135], v[142:143], v[142:143] op_sel:[0,1] op_sel_hi:[1,0]
	v_pk_add_f32 v[142:143], v[146:147], v[146:147] op_sel:[0,1] op_sel_hi:[1,0]
	v_pk_add_f32 v[146:147], v[150:151], v[154:155]
	v_pk_add_f32 v[148:149], v[148:149], v[162:163]
	v_pk_add_f32 v[150:151], v[156:157], v[166:167]
	v_mul_f32_e32 v174, v126, v126
	v_mul_f32_e32 v175, v127, v127
	v_mul_f32_e32 v176, v128, v128
	v_mul_f32_e32 v177, v129, v129
	v_pk_fma_f32 v[158:159], v[130:131], v[130:131], v[168:169] op_sel_hi:[1,1,0]
	v_pk_fma_f32 v[160:161], v[132:133], v[132:133], v[170:171] op_sel_hi:[1,1,0]
	v_pk_add_f32 v[78:79], v[78:79], v[136:137]
	v_pk_add_f32 v[136:137], v[138:139], v[140:141]
	v_mov_b32_e32 v135, v51
	v_mov_b32_e32 v143, v153
	v_pk_add_f32 v[138:139], v[148:149], v[148:149] op_sel:[0,1] op_sel_hi:[1,0]
	v_pk_add_f32 v[140:141], v[150:151], v[150:151] op_sel:[0,1] op_sel_hi:[1,0]
	v_mov_b32_e32 v159, v176
	v_mov_b32_e32 v161, v177
	v_pk_add_f32 v[134:135], v[134:135], v[142:143]
	v_mov_b32_e32 v139, v174
	v_mov_b32_e32 v141, v175
	v_pk_add_f32 v[148:149], v[158:159], v[160:161]
	v_pk_add_f32 v[136:137], v[136:137], v[144:145]
	v_pk_add_f32 v[134:135], v[134:135], v[146:147]
	v_pk_add_f32 v[138:139], v[138:139], v[140:141]
	v_mov_b32_e32 v143, v136
	v_mov_b32_e32 v142, v134
	v_mov_b32_e32 v136, v135
	v_pk_add_f32 v[134:135], v[138:139], v[148:149]
	v_mov_b32_e32 v150, v78
	v_pk_add_f32 v[136:137], v[142:143], v[136:137]
	v_mov_b32_e32 v151, v134
	v_mov_b32_e32 v134, v79
	ds_bpermute_b32 v79, v80, v137
	ds_bpermute_b32 v78, v80, v136
	v_pk_add_f32 v[134:135], v[150:151], v[134:135]
	ds_bpermute_b32 v139, v80, v135
	ds_bpermute_b32 v138, v80, v134
	s_waitcnt lgkmcnt(2)
	v_pk_add_f32 v[78:79], v[136:137], v[78:79]
	ds_bpermute_b32 v137, v81, v79
	ds_bpermute_b32 v136, v81, v78
	s_waitcnt lgkmcnt(2)
	v_pk_add_f32 v[134:135], v[134:135], v[138:139]
	ds_bpermute_b32 v139, v81, v135
	ds_bpermute_b32 v138, v81, v134
	s_waitcnt lgkmcnt(2)
	v_pk_add_f32 v[78:79], v[78:79], v[136:137]
	ds_bpermute_b32 v137, v82, v79
	ds_bpermute_b32 v136, v82, v78
	s_waitcnt lgkmcnt(2)
	v_pk_add_f32 v[134:135], v[134:135], v[138:139]
	ds_bpermute_b32 v139, v82, v135
	ds_bpermute_b32 v138, v82, v134
	s_waitcnt lgkmcnt(2)
	v_pk_add_f32 v[78:79], v[78:79], v[136:137]
	ds_bpermute_b32 v137, v83, v79
	ds_bpermute_b32 v136, v83, v78
	s_waitcnt lgkmcnt(2)
	v_pk_add_f32 v[134:135], v[134:135], v[138:139]
	ds_bpermute_b32 v139, v83, v135
	ds_bpermute_b32 v138, v83, v134
	s_waitcnt lgkmcnt(2)
	v_pk_add_f32 v[78:79], v[78:79], v[136:137]
	ds_bpermute_b32 v137, v84, v79
	ds_bpermute_b32 v136, v84, v78
	s_waitcnt lgkmcnt(2)
	v_pk_add_f32 v[134:135], v[134:135], v[138:139]
	ds_bpermute_b32 v139, v84, v135
	ds_bpermute_b32 v138, v84, v134
	s_waitcnt lgkmcnt(2)
	v_pk_add_f32 v[78:79], v[78:79], v[136:137]
	ds_bpermute_b32 v137, v85, v79
	ds_bpermute_b32 v136, v85, v78
	s_waitcnt lgkmcnt(2)
	v_pk_add_f32 v[134:135], v[134:135], v[138:139]
	ds_bpermute_b32 v139, v85, v135
	ds_bpermute_b32 v138, v85, v134
	s_waitcnt lgkmcnt(2)
	v_pk_add_f32 v[78:79], v[78:79], v[136:137]
	s_nop 0
	v_pk_fma_f32 v[78:79], v[78:79], s[24:25], v[76:77] op_sel_hi:[1,0,0]
	s_waitcnt lgkmcnt(0)
	v_pk_add_f32 v[134:135], v[134:135], v[138:139]
	v_mul_f32_e32 v37, 0x4b800000, v79
	v_mul_f32_e32 v39, 0x4b800000, v78
	v_cmp_gt_f32_e32 vcc, s39, v78
	v_pk_fma_f32 v[76:77], v[134:135], s[24:25], v[76:77] op_sel_hi:[1,0,0]
	v_cmp_gt_f32_e64 s[0:1], s39, v79
	v_cndmask_b32_e32 v39, v78, v39, vcc
	v_mul_f32_e32 v51, 0x4b800000, v77
	v_cndmask_b32_e64 v37, v79, v37, s[0:1]
	v_cmp_gt_f32_e64 s[6:7], s39, v77
	v_mul_f32_e32 v78, 0x4b800000, v76
	v_cmp_gt_f32_e64 s[4:5], s39, v76
	v_rsq_f32_e32 v37, v37
	v_rsq_f32_e32 v39, v39
	v_cndmask_b32_e64 v51, v77, v51, s[6:7]
	v_cndmask_b32_e64 v76, v76, v78, s[4:5]
	v_rsq_f32_e32 v51, v51
	v_rsq_f32_e32 v134, v76
	v_mul_f32_e32 v76, 0x45800000, v37
	v_mul_f32_e32 v77, 0x45800000, v39
	v_cndmask_b32_e64 v76, v37, v76, s[0:1]
	v_cndmask_b32_e32 v78, v39, v77, vcc
	v_mul_f32_e32 v37, 0x45800000, v51
	v_mul_f32_e32 v39, 0x45800000, v134
	v_pk_mul_f32 v[86:87], v[86:87], v[76:77] op_sel_hi:[1,0]
	v_pk_mul_f32 v[88:89], v[88:89], v[76:77] op_sel_hi:[1,0]
	v_pk_mul_f32 v[90:91], v[90:91], v[76:77] op_sel_hi:[1,0]
	v_pk_mul_f32 v[92:93], v[92:93], v[76:77] op_sel_hi:[1,0]
	v_pk_mul_f32 v[98:99], v[98:99], v[76:77] op_sel_hi:[1,0]
	v_pk_mul_f32 v[100:101], v[100:101], v[76:77] op_sel_hi:[1,0]
	v_pk_mul_f32 v[94:95], v[94:95], v[76:77] op_sel_hi:[1,0]
	v_pk_mul_f32 v[76:77], v[96:97], v[76:77] op_sel_hi:[1,0]
	v_pk_mul_f32 v[96:97], v[102:103], v[78:79] op_sel_hi:[1,0]
	v_pk_mul_f32 v[102:103], v[104:105], v[78:79] op_sel_hi:[1,0]
	v_pk_mul_f32 v[104:105], v[106:107], v[78:79] op_sel_hi:[1,0]
	v_pk_mul_f32 v[106:107], v[108:109], v[78:79] op_sel_hi:[1,0]
	v_pk_mul_f32 v[108:109], v[114:115], v[78:79] op_sel_hi:[1,0]
	v_pk_mul_f32 v[114:115], v[116:117], v[78:79] op_sel_hi:[1,0]
	v_pk_mul_f32 v[110:111], v[110:111], v[78:79] op_sel_hi:[1,0]
	v_pk_mul_f32 v[78:79], v[112:113], v[78:79] op_sel_hi:[1,0]
	v_cndmask_b32_e64 v112, v51, v37, s[6:7]
	v_cndmask_b32_e64 v116, v134, v39, s[4:5]
	v_pk_fma_f32 v[88:89], v[58:59], v[88:89], v[10:11]
	v_pk_fma_f32 v[86:87], v[60:61], v[86:87], v[8:9]
	v_pk_fma_f32 v[90:91], v[64:65], v[90:91], v[0:1]
	v_pk_fma_f32 v[100:101], v[66:67], v[100:101], v[6:7]
	v_pk_fma_f32 v[98:99], v[68:69], v[98:99], v[4:5]
	v_pk_fma_f32 v[78:79], v[70:71], v[78:79], v[14:15]
; __device__ __forceinline__ unsigned pk2(float lo, float hi) { f32x2 v = {lo, hi}; bf16x2_t b = __builtin_convertvector(v, bf16x2_t); return __builtin_bit_cast(unsigned, b); }
; __device__ __forceinline__ void norm_rows(const float* x, int nrows, const float* g, const float* sc, const float* sh, bf16_t* o, int lane) {
;     ...
;             u32x2* op = (u32x2*)(o + (size_t)(r0 + rr) * 1024) + lane;
; #pragma unroll
;             for (int j = 0; j < 4; ++j) { const f32x4 y = v[rr][j] * rstd * gs[j] + shv[j]; u32x2 wv; wv.x = pk2(y.x, y.y); wv.y = pk2(y.z, y.w); op[64 * j] = wv; } }
; __device__ __forceinline__ void norm_phase(const Args& a, const float* x, int layer, int which  , bool with_ctx) {
;     ...
;     if (with_ctx) { const float* mb = MOD + (size_t)8 * 6144;
;         for (int row = gw; row < MCTX; row += NGW) norm_rows(a.in[2] + (size_t)row * 1024, 1, g, mb + (c0 + 1) * 1024, mb + c0 * 1024, XN + (size_t)(M_ + row) * 1024, lane); }
	v_pk_mul_f32 v[118:119], v[118:119], v[112:113] op_sel_hi:[1,0]
	v_pk_mul_f32 v[120:121], v[120:121], v[112:113] op_sel_hi:[1,0]
	v_pk_fma_f32 v[92:93], v[62:63], v[92:93], v[2:3]
	v_pk_fma_f32 v[76:77], v[70:71], v[76:77], v[14:15]
	v_pk_fma_f32 v[94:95], v[72:73], v[94:95], v[12:13]
	v_pk_fma_f32 v[102:103], v[58:59], v[102:103], v[10:11]
	v_pk_fma_f32 v[96:97], v[60:61], v[96:97], v[8:9]
	v_pk_fma_f32 v[106:107], v[62:63], v[106:107], v[2:3]
	v_pk_fma_f32 v[104:105], v[64:65], v[104:105], v[0:1]
	v_pk_fma_f32 v[114:115], v[66:67], v[114:115], v[6:7]
	v_pk_fma_f32 v[108:109], v[68:69], v[108:109], v[4:5]
	v_pk_fma_f32 v[110:111], v[72:73], v[110:111], v[12:13]
	v_pk_mul_f32 v[122:123], v[122:123], v[112:113] op_sel_hi:[1,0]
	v_pk_mul_f32 v[124:125], v[124:125], v[112:113] op_sel_hi:[1,0]
	v_pk_mul_f32 v[130:131], v[130:131], v[112:113] op_sel_hi:[1,0]
	v_pk_mul_f32 v[132:133], v[132:133], v[112:113] op_sel_hi:[1,0]
	v_pk_mul_f32 v[126:127], v[126:127], v[112:113] op_sel_hi:[1,0]
	v_pk_mul_f32 v[112:113], v[128:129], v[112:113] op_sel_hi:[1,0]
	v_pk_mul_f32 v[28:29], v[28:29], v[116:117] op_sel_hi:[1,0]
	v_pk_mul_f32 v[30:31], v[30:31], v[116:117] op_sel_hi:[1,0]
	v_pk_mul_f32 v[24:25], v[24:25], v[116:117] op_sel_hi:[1,0]
	v_pk_mul_f32 v[26:27], v[26:27], v[116:117] op_sel_hi:[1,0]
	v_pk_mul_f32 v[20:21], v[20:21], v[116:117] op_sel_hi:[1,0]
	v_pk_mul_f32 v[22:23], v[22:23], v[116:117] op_sel_hi:[1,0]
	v_pk_mul_f32 v[16:17], v[16:17], v[116:117] op_sel_hi:[1,0]
	v_pk_mul_f32 v[18:19], v[18:19], v[116:117] op_sel_hi:[1,0]
	v_cvt_pk_bf16_f32 v86, v86, v87
	v_cvt_pk_bf16_f32 v87, v88, v89
	v_cvt_pk_bf16_f32 v88, v90, v91
	v_cvt_pk_bf16_f32 v90, v98, v99
	v_cvt_pk_bf16_f32 v91, v100, v101
	v_cvt_pk_bf16_f32 v99, v78, v79
	v_pk_fma_f32 v[78:79], v[58:59], v[120:121], v[10:11]
	v_pk_fma_f32 v[100:101], v[60:61], v[118:119], v[8:9]
	v_cvt_pk_bf16_f32 v89, v92, v93
	v_cvt_pk_bf16_f32 v92, v94, v95
	v_cvt_pk_bf16_f32 v93, v76, v77
	v_cvt_pk_bf16_f32 v76, v96, v97
	v_cvt_pk_bf16_f32 v77, v102, v103
	v_cvt_pk_bf16_f32 v94, v104, v105
	v_cvt_pk_bf16_f32 v95, v106, v107
	v_cvt_pk_bf16_f32 v96, v108, v109
	v_cvt_pk_bf16_f32 v97, v114, v115
	v_cvt_pk_bf16_f32 v98, v110, v111
	v_pk_fma_f32 v[102:103], v[62:63], v[124:125], v[2:3]
	v_pk_fma_f32 v[104:105], v[64:65], v[122:123], v[0:1]
	v_pk_fma_f32 v[106:107], v[66:67], v[132:133], v[6:7]
	v_pk_fma_f32 v[108:109], v[68:69], v[130:131], v[4:5]
	v_pk_fma_f32 v[110:111], v[70:71], v[112:113], v[14:15]
	v_pk_fma_f32 v[112:113], v[72:73], v[126:127], v[12:13]
	v_pk_fma_f32 v[30:31], v[58:59], v[30:31], v[10:11]
	v_pk_fma_f32 v[28:29], v[60:61], v[28:29], v[8:9]
	v_pk_fma_f32 v[26:27], v[62:63], v[26:27], v[2:3]
	v_pk_fma_f32 v[24:25], v[64:65], v[24:25], v[0:1]
	v_pk_fma_f32 v[22:23], v[66:67], v[22:23], v[6:7]
	v_pk_fma_f32 v[20:21], v[68:69], v[20:21], v[4:5]
	v_pk_fma_f32 v[18:19], v[70:71], v[18:19], v[14:15]
	v_pk_fma_f32 v[16:17], v[72:73], v[16:17], v[12:13]
	global_store_dwordx2 v[74:75], v[86:87], off offset:-3584
	global_store_dwordx2 v[74:75], v[88:89], off offset:-3072
	global_store_dwordx2 v[74:75], v[90:91], off offset:-2560
	global_store_dwordx2 v[74:75], v[92:93], off offset:-2048
	global_store_dwordx2 v[74:75], v[76:77], off offset:-1536
	global_store_dwordx2 v[74:75], v[94:95], off offset:-1024
	global_store_dwordx2 v[74:75], v[96:97], off offset:-512
	global_store_dwordx2 v[54:55], v[98:99], off offset:-4096
	v_cvt_pk_bf16_f32 v74, v100, v101
	v_cvt_pk_bf16_f32 v75, v78, v79
	v_cvt_pk_bf16_f32 v76, v104, v105
	v_cvt_pk_bf16_f32 v77, v102, v103
	v_cvt_pk_bf16_f32 v78, v108, v109
	v_cvt_pk_bf16_f32 v79, v106, v107
	v_cvt_pk_bf16_f32 v86, v112, v113
	v_cvt_pk_bf16_f32 v87, v110, v111
	v_cvt_pk_bf16_f32 v28, v28, v29
	v_cvt_pk_bf16_f32 v29, v30, v31
	v_cvt_pk_bf16_f32 v24, v24, v25
	v_cvt_pk_bf16_f32 v25, v26, v27
	v_cvt_pk_bf16_f32 v20, v20, v21
	v_cvt_pk_bf16_f32 v21, v22, v23
	v_cvt_pk_bf16_f32 v16, v16, v17
	v_cvt_pk_bf16_f32 v17, v18, v19
	global_store_dwordx2 v[54:55], v[74:75], off offset:-3584
	global_store_dwordx2 v[54:55], v[76:77], off offset:-3072
	global_store_dwordx2 v[54:55], v[78:79], off offset:-2560
	global_store_dwordx2 v[54:55], v[86:87], off offset:-2048
	global_store_dwordx2 v[54:55], v[28:29], off offset:-1536
	global_store_dwordx2 v[54:55], v[24:25], off offset:-1024
	global_store_dwordx2 v[54:55], v[20:21], off offset:-512
	global_store_dwordx2 v[54:55], v[16:17], off
	v_lshl_add_u64 v[54:55], v[54:55], 0, s[42:43]
	s_cbranch_scc1 .LBB0_316
	v_add_u32_e32 v33, s10, v33
	v_cmp_lt_i32_e32 vcc, s46, v33
	s_or_b64 s[12:13], vcc, s[12:13]
	v_add_u32_e32 v50, s11, v50
	s_andn2_b64 exec, exec, s[12:13]
	s_cbranch_execnz .LBB0_315
	s_or_b64 exec, exec, s[12:13]
	s_add_u32 s0, s28, 0x30000
	s_addc_u32 s1, s29, 0
	v_ashrrev_i32_e32 v33, 31, v32
	v_mov_b32_e32 v39, 0
	s_add_u32 s4, s28, 0x31000
	v_lshlrev_b64 v[18:19], 12, v[32:33]
	s_addc_u32 s5, s29, 0
	v_mov_b32_e32 v47, v39
	v_mov_b32_e32 v45, v39
	v_mov_b32_e32 v43, v39
	v_mov_b32_e32 v41, v39
	v_or_b32_e32 v18, v18, v36
	s_ashr_i32 s11, s10, 31
	v_lshl_add_u64 v[0:1], s[16:17], 0, v[38:39]
	v_lshl_add_u64 v[2:3], s[4:5], 0, v[46:47]
	v_lshl_add_u64 v[4:5], s[0:1], 0, v[46:47]
	v_lshl_add_u64 v[6:7], s[4:5], 0, v[44:45]
	v_lshl_add_u64 v[8:9], s[0:1], 0, v[44:45]
	v_lshl_add_u64 v[10:11], s[4:5], 0, v[42:43]
	v_lshl_add_u64 v[12:13], s[0:1], 0, v[42:43]
	v_lshl_add_u64 v[14:15], s[4:5], 0, v[40:41]
	v_lshl_add_u64 v[16:17], s[0:1], 0, v[40:41]
	v_lshl_add_u64 v[18:19], s[40:41], 0, v[18:19]
	s_lshl_b64 s[0:1], s[10:11], 12
	s_mov_b64 s[4:5], 0
	v_mov_b32_e32 v20, 0x358637bd
	s_mov_b32 s6, 0x800000
	s_movk_i32 s7, 0x7ff

; __device__ __forceinline__ unsigned pk2(float lo, float hi) { f32x2 v = {lo, hi}; bf16x2_t b = __builtin_convertvector(v, bf16x2_t); return __builtin_bit_cast(unsigned, b); }
;     __device__ __forceinline__ void operator()(const f32x4 (&acc)[2][2][4][2], const Unit& u, int wr, int wc, int fr, int fq) const {
;     ...
;         for (int bj = 0; bj < 2; ++bj) { const int c = col0 + bj * HALF;
;             const f32x4 g0 = *(const f32x4*)(gp + c), g1 = *(const f32x4*)(gp + c + 4);
;             const f32x4 b0 = bias ? *(const f32x4*)(bias + c) : (f32x4){0.f, 0.f, 0.f, 0.f}, b1 = bias ? *(const f32x4*)(bias + c + 4) : (f32x4){0.f, 0.f, 0.f, 0.f};
; #pragma unroll
;             for (int ai = 0; ai < 2; ++ai)
; #pragma unroll
;                 for (int m = 0; m < 4; ++m) { const size_t off = (size_t)(row0 + ai * HALF + m * 16) * 1024 + c;
;                     f32x4 x0, x1;
;                     if (BASE_BF16) { const u32x4 v = *(const u32x4*)((const bf16_t*)base + off);
;                         x0 = (f32x4){__uint_as_float(v.x << 16), __uint_as_float(v.x & 0xffff0000u), __uint_as_float(v.y << 16), __uint_as_float(v.y & 0xffff0000u)};
;                         x1 = (f32x4){__uint_as_float(v.z << 16), __uint_as_float(v.z & 0xffff0000u), __uint_as_float(v.w << 16), __uint_as_float(v.w & 0xffff0000u)}; }
;                     else { x0 = *(const f32x4*)((const float*)base + off); x1 = *(const f32x4*)((const float*)base + off + 4); }
;                     x0 = x0 + g0 * (acc[ai][bj][m][0] + b0); x1 = x1 + g1 * (acc[ai][bj][m][1] + b1);
;                     if (OUT_BF16) { u32x4 w; w.x = pk2(x0[0], x0[1]); w.y = pk2(x0[2], x0[3]); w.z = pk2(x1[0], x1[1]); w.w = pk2(x1[2], x1[3]); *(u32x4*)((bf16_t*)out + off) = w; }
;                     else { *(f32x4*)((float*)out + off) = x0; *(f32x4*)((float*)out + off + 4) = x1; } } }
.LBB0_593:
	v_lshl_add_u32 v176, s52, 8, v162
	v_lshl_or_b32 v154, s83, 8, v164
	s_ashr_i32 s33, s52, 5
	v_ashrrev_i32_e32 v177, 31, v176
	s_mul_hi_i32 s34, s33, 0x6000
	s_mulk_i32 s33, 0x6000
	v_lshlrev_b64 v[156:157], 10, v[176:177]
	v_ashrrev_i32_e32 v155, 31, v154
	s_add_u32 s54, s76, s33
	v_lshl_add_u64 v[178:179], v[156:157], 0, v[154:155]
	s_addc_u32 s55, s77, s34
	v_lshl_add_u64 v[160:161], v[178:179], 2, s[36:37]
	v_lshl_add_u64 v[158:159], v[154:155], 2, s[54:55]
	global_load_dwordx4 v[168:171], v[160:161], off nt
	global_load_dwordx4 v[132:135], v[158:159], off
	global_load_dwordx4 v[128:131], v[158:159], off offset:16
	global_load_dwordx4 v[172:175], v[160:161], off offset:16 nt
	v_pk_add_f32 v[182:183], v[120:121], 0 op_sel_hi:[1,0]
	v_or_b32_e32 v120, 16, v176
	v_pk_add_f32 v[126:127], v[126:127], 0 op_sel_hi:[1,0]
	v_pk_add_f32 v[124:125], v[124:125], 0 op_sel_hi:[1,0]
	v_pk_add_f32 v[180:181], v[122:123], 0 op_sel_hi:[1,0]
	v_ashrrev_i32_e32 v121, 31, v120
	v_lshlrev_b64 v[120:121], 10, v[120:121]
	v_lshl_add_u64 v[178:179], v[178:179], 1, s[8:9]
	v_lshl_add_u64 v[184:185], v[120:121], 0, v[154:155]
	v_lshl_add_u64 v[122:123], v[184:185], 2, s[36:37]
	v_pk_add_f32 v[118:119], v[118:119], 0 op_sel_hi:[1,0]
	v_pk_add_f32 v[116:117], v[116:117], 0 op_sel_hi:[1,0]
	v_pk_add_f32 v[110:111], v[110:111], 0 op_sel_hi:[1,0]
	v_pk_add_f32 v[108:109], v[108:109], 0 op_sel_hi:[1,0]
	v_pk_add_f32 v[102:103], v[102:103], 0 op_sel_hi:[1,0]
	v_pk_add_f32 v[100:101], v[100:101], 0 op_sel_hi:[1,0]
	v_pk_add_f32 v[94:95], v[94:95], 0 op_sel_hi:[1,0]
	v_pk_add_f32 v[92:93], v[92:93], 0 op_sel_hi:[1,0]
	v_pk_add_f32 v[86:87], v[86:87], 0 op_sel_hi:[1,0]
	v_pk_add_f32 v[84:85], v[84:85], 0 op_sel_hi:[1,0]
	v_pk_add_f32 v[78:79], v[78:79], 0 op_sel_hi:[1,0]
	v_pk_add_f32 v[76:77], v[76:77], 0 op_sel_hi:[1,0]
	v_pk_add_f32 v[66:67], v[66:67], 0 op_sel_hi:[1,0]
	v_pk_add_f32 v[64:65], v[64:65], 0 op_sel_hi:[1,0]
	v_pk_add_f32 v[58:59], v[58:59], 0 op_sel_hi:[1,0]
	v_pk_add_f32 v[56:57], v[56:57], 0 op_sel_hi:[1,0]
	v_pk_add_f32 v[70:71], v[70:71], 0 op_sel_hi:[1,0]
	v_pk_add_f32 v[68:69], v[68:69], 0 op_sel_hi:[1,0]
	v_pk_add_f32 v[62:63], v[62:63], 0 op_sel_hi:[1,0]
	v_pk_add_f32 v[54:55], v[54:55], 0 op_sel_hi:[1,0]
	v_pk_add_f32 v[52:53], v[52:53], 0 op_sel_hi:[1,0]
	v_pk_add_f32 v[50:51], v[50:51], 0 op_sel_hi:[1,0]
	v_pk_add_f32 v[48:49], v[48:49], 0 op_sel_hi:[1,0]
	v_pk_add_f32 v[46:47], v[46:47], 0 op_sel_hi:[1,0]
	v_pk_add_f32 v[44:45], v[44:45], 0 op_sel_hi:[1,0]
	v_pk_add_f32 v[42:43], v[42:43], 0 op_sel_hi:[1,0]
	v_pk_add_f32 v[40:41], v[40:41], 0 op_sel_hi:[1,0]
	v_pk_add_f32 v[38:39], v[38:39], 0 op_sel_hi:[1,0]
	v_pk_add_f32 v[36:37], v[36:37], 0 op_sel_hi:[1,0]
	v_pk_add_f32 v[34:35], v[34:35], 0 op_sel_hi:[1,0]
	v_pk_add_f32 v[32:33], v[32:33], 0 op_sel_hi:[1,0]
	v_pk_add_f32 v[30:31], v[30:31], 0 op_sel_hi:[1,0]
	v_pk_add_f32 v[28:29], v[28:29], 0 op_sel_hi:[1,0]
	v_pk_add_f32 v[26:27], v[26:27], 0 op_sel_hi:[1,0]
	v_pk_add_f32 v[24:25], v[24:25], 0 op_sel_hi:[1,0]
	v_pk_add_f32 v[22:23], v[22:23], 0 op_sel_hi:[1,0]
	v_pk_add_f32 v[20:21], v[20:21], 0 op_sel_hi:[1,0]
	v_pk_add_f32 v[18:19], v[18:19], 0 op_sel_hi:[1,0]
	v_pk_add_f32 v[16:17], v[16:17], 0 op_sel_hi:[1,0]
	v_pk_add_f32 v[14:15], v[14:15], 0 op_sel_hi:[1,0]
	v_pk_add_f32 v[12:13], v[12:13], 0 op_sel_hi:[1,0]
	v_pk_add_f32 v[10:11], v[10:11], 0 op_sel_hi:[1,0]
	v_pk_add_f32 v[8:9], v[8:9], 0 op_sel_hi:[1,0]
	v_pk_add_f32 v[6:7], v[6:7], 0 op_sel_hi:[1,0]
	v_pk_add_f32 v[4:5], v[4:5], 0 op_sel_hi:[1,0]
	v_pk_add_f32 v[2:3], v[2:3], 0 op_sel_hi:[1,0]
	v_pk_add_f32 v[0:1], v[0:1], 0 op_sel_hi:[1,0]
	s_andn2_b64 vcc, exec, s[0:1]
	s_mov_b64 s[0:1], -1
	s_waitcnt vmcnt(0)
	v_pk_fma_f32 v[126:127], v[126:127], v[134:135], v[170:171]
	v_pk_fma_f32 v[124:125], v[124:125], v[132:133], v[168:169]
	v_pk_fma_f32 v[168:169], v[180:181], v[130:131], v[174:175]
	v_pk_fma_f32 v[170:171], v[182:183], v[128:129], v[172:173]
	v_cvt_pk_bf16_f32 v124, v124, v125
	v_cvt_pk_bf16_f32 v125, v126, v127
	v_cvt_pk_bf16_f32 v126, v170, v171
	v_cvt_pk_bf16_f32 v127, v168, v169
	global_store_dwordx4 v[178:179], v[124:127], off
	global_load_dwordx4 v[124:127], v[122:123], off nt
	s_nop 0
	global_load_dwordx4 v[168:171], v[122:123], off offset:16 nt
	v_pk_add_f32 v[174:175], v[112:113], 0 op_sel_hi:[1,0]
	v_or_b32_e32 v112, 32, v176
	v_pk_add_f32 v[172:173], v[114:115], 0 op_sel_hi:[1,0]
	v_ashrrev_i32_e32 v113, 31, v112
	v_lshlrev_b64 v[112:113], 10, v[112:113]
	v_lshl_add_u64 v[178:179], v[112:113], 0, v[154:155]
	v_lshl_add_u64 v[180:181], v[184:185], 1, s[8:9]
	v_lshl_add_u64 v[114:115], v[178:179], 2, s[36:37]
	s_waitcnt vmcnt(1)
	v_pk_fma_f32 v[118:119], v[118:119], v[134:135], v[126:127]
	v_pk_fma_f32 v[116:117], v[116:117], v[132:133], v[124:125]
	s_waitcnt vmcnt(0)
	v_pk_fma_f32 v[124:125], v[172:173], v[130:131], v[170:171]
	v_pk_fma_f32 v[126:127], v[174:175], v[128:129], v[168:169]
	v_cvt_pk_bf16_f32 v116, v116, v117
	v_cvt_pk_bf16_f32 v117, v118, v119
	v_cvt_pk_bf16_f32 v118, v126, v127
	v_cvt_pk_bf16_f32 v119, v124, v125
	global_store_dwordx4 v[180:181], v[116:119], off
	global_load_dwordx4 v[116:119], v[114:115], off nt
	s_nop 0
	global_load_dwordx4 v[124:127], v[114:115], off offset:16 nt
	v_pk_add_f32 v[170:171], v[104:105], 0 op_sel_hi:[1,0]
	v_or_b32_e32 v104, 48, v176
	v_pk_add_f32 v[168:169], v[106:107], 0 op_sel_hi:[1,0]
	v_ashrrev_i32_e32 v105, 31, v104
	v_lshlrev_b64 v[104:105], 10, v[104:105]
	v_lshl_add_u64 v[172:173], v[104:105], 0, v[154:155]
	v_lshl_add_u64 v[174:175], v[178:179], 1, s[8:9]
	v_lshl_add_u64 v[106:107], v[172:173], 2, s[36:37]
	s_waitcnt vmcnt(1)
; __device__ __forceinline__ unsigned pk2(float lo, float hi) { f32x2 v = {lo, hi}; bf16x2_t b = __builtin_convertvector(v, bf16x2_t); return __builtin_bit_cast(unsigned, b); }
;     __device__ __forceinline__ void operator()(const f32x4 (&acc)[2][2][4][2], const Unit& u, int wr, int wc, int fr, int fq) const {
;     ...
;         for (int bj = 0; bj < 2; ++bj) { const int c = col0 + bj * HALF;
;             const f32x4 g0 = *(const f32x4*)(gp + c), g1 = *(const f32x4*)(gp + c + 4);
;             const f32x4 b0 = bias ? *(const f32x4*)(bias + c) : (f32x4){0.f, 0.f, 0.f, 0.f}, b1 = bias ? *(const f32x4*)(bias + c + 4) : (f32x4){0.f, 0.f, 0.f, 0.f};
; #pragma unroll
;             for (int ai = 0; ai < 2; ++ai)
; #pragma unroll
;                 for (int m = 0; m < 4; ++m) { const size_t off = (size_t)(row0 + ai * HALF + m * 16) * 1024 + c;
;                     f32x4 x0, x1;
;                     if (BASE_BF16) { const u32x4 v = *(const u32x4*)((const bf16_t*)base + off);
;                         x0 = (f32x4){__uint_as_float(v.x << 16), __uint_as_float(v.x & 0xffff0000u), __uint_as_float(v.y << 16), __uint_as_float(v.y & 0xffff0000u)};
;                         x1 = (f32x4){__uint_as_float(v.z << 16), __uint_as_float(v.z & 0xffff0000u), __uint_as_float(v.w << 16), __uint_as_float(v.w & 0xffff0000u)}; }
;                     else { x0 = *(const f32x4*)((const float*)base + off); x1 = *(const f32x4*)((const float*)base + off + 4); }
;                     x0 = x0 + g0 * (acc[ai][bj][m][0] + b0); x1 = x1 + g1 * (acc[ai][bj][m][1] + b1);
;                     if (OUT_BF16) { u32x4 w; w.x = pk2(x0[0], x0[1]); w.y = pk2(x0[2], x0[3]); w.z = pk2(x1[0], x1[1]); w.w = pk2(x1[2], x1[3]); *(u32x4*)((bf16_t*)out + off) = w; }
;                     else { *(f32x4*)((float*)out + off) = x0; *(f32x4*)((float*)out + off + 4) = x1; } } }
	v_pk_fma_f32 v[110:111], v[110:111], v[134:135], v[118:119]
	v_pk_fma_f32 v[108:109], v[108:109], v[132:133], v[116:117]
	s_waitcnt vmcnt(0)
	v_pk_fma_f32 v[116:117], v[168:169], v[130:131], v[126:127]
	v_pk_fma_f32 v[118:119], v[170:171], v[128:129], v[124:125]
	v_cvt_pk_bf16_f32 v108, v108, v109
	v_cvt_pk_bf16_f32 v109, v110, v111
	v_cvt_pk_bf16_f32 v110, v118, v119
	v_cvt_pk_bf16_f32 v111, v116, v117
	global_store_dwordx4 v[174:175], v[108:111], off
	global_load_dwordx4 v[108:111], v[106:107], off nt
	s_nop 0
	global_load_dwordx4 v[116:119], v[106:107], off offset:16 nt
	v_pk_add_f32 v[124:125], v[98:99], 0 op_sel_hi:[1,0]
	v_pk_add_f32 v[126:127], v[96:97], 0 op_sel_hi:[1,0]
	v_lshl_add_u64 v[96:97], v[156:157], 0, s[20:21]
	v_lshl_add_u64 v[168:169], v[96:97], 0, v[154:155]
	v_lshl_add_u64 v[170:171], v[172:173], 1, s[8:9]
	v_lshl_add_u64 v[98:99], v[168:169], 2, s[36:37]
	s_waitcnt vmcnt(1)
	v_pk_fma_f32 v[102:103], v[102:103], v[134:135], v[110:111]
	v_pk_fma_f32 v[100:101], v[100:101], v[132:133], v[108:109]
	s_waitcnt vmcnt(0)
	v_pk_fma_f32 v[108:109], v[124:125], v[130:131], v[118:119]
	v_pk_fma_f32 v[110:111], v[126:127], v[128:129], v[116:117]
	v_cvt_pk_bf16_f32 v100, v100, v101
	v_cvt_pk_bf16_f32 v101, v102, v103
	v_cvt_pk_bf16_f32 v102, v110, v111
	v_cvt_pk_bf16_f32 v103, v108, v109
	global_store_dwordx4 v[170:171], v[100:103], off
	global_load_dwordx4 v[100:103], v[98:99], off nt
	s_nop 0
	global_load_dwordx4 v[108:111], v[98:99], off offset:16 nt
	v_pk_add_f32 v[116:117], v[90:91], 0 op_sel_hi:[1,0]
	v_pk_add_f32 v[118:119], v[88:89], 0 op_sel_hi:[1,0]
	v_lshl_add_u64 v[88:89], v[156:157], 0, s[22:23]
	v_lshl_add_u64 v[124:125], v[88:89], 0, v[154:155]
	v_lshl_add_u64 v[126:127], v[168:169], 1, s[8:9]
	v_lshl_add_u64 v[90:91], v[124:125], 2, s[36:37]
	s_waitcnt vmcnt(1)
	v_pk_fma_f32 v[94:95], v[94:95], v[134:135], v[102:103]
	v_pk_fma_f32 v[92:93], v[92:93], v[132:133], v[100:101]
	s_waitcnt vmcnt(0)
	v_pk_fma_f32 v[100:101], v[116:117], v[130:131], v[110:111]
	v_pk_fma_f32 v[102:103], v[118:119], v[128:129], v[108:109]
	v_cvt_pk_bf16_f32 v92, v92, v93
	v_cvt_pk_bf16_f32 v93, v94, v95
	v_cvt_pk_bf16_f32 v94, v102, v103
	v_cvt_pk_bf16_f32 v95, v100, v101
	global_store_dwordx4 v[126:127], v[92:95], off
	global_load_dwordx4 v[92:95], v[90:91], off nt
	s_nop 0
	global_load_dwordx4 v[100:103], v[90:91], off offset:16 nt
	v_pk_add_f32 v[108:109], v[82:83], 0 op_sel_hi:[1,0]
	v_pk_add_f32 v[110:111], v[80:81], 0 op_sel_hi:[1,0]
	v_lshl_add_u64 v[80:81], v[156:157], 0, s[24:25]
	v_lshl_add_u64 v[116:117], v[80:81], 0, v[154:155]
	v_lshl_add_u64 v[118:119], v[124:125], 1, s[8:9]
	v_lshl_add_u64 v[82:83], v[116:117], 2, s[36:37]
	s_waitcnt vmcnt(1)
	v_pk_fma_f32 v[86:87], v[86:87], v[134:135], v[94:95]
	v_pk_fma_f32 v[84:85], v[84:85], v[132:133], v[92:93]
	s_waitcnt vmcnt(0)
	v_pk_fma_f32 v[92:93], v[108:109], v[130:131], v[102:103]
	v_pk_fma_f32 v[94:95], v[110:111], v[128:129], v[100:101]
	v_cvt_pk_bf16_f32 v84, v84, v85
	v_cvt_pk_bf16_f32 v85, v86, v87
	v_cvt_pk_bf16_f32 v86, v94, v95
	v_cvt_pk_bf16_f32 v87, v92, v93
	global_store_dwordx4 v[118:119], v[84:87], off
	global_load_dwordx4 v[84:87], v[82:83], off nt
	s_nop 0
	global_load_dwordx4 v[92:95], v[82:83], off offset:16 nt
	v_pk_add_f32 v[100:101], v[74:75], 0 op_sel_hi:[1,0]
	v_pk_add_f32 v[102:103], v[72:73], 0 op_sel_hi:[1,0]
	v_lshl_add_u64 v[72:73], v[156:157], 0, s[38:39]
	v_lshl_add_u64 v[108:109], v[72:73], 0, v[154:155]
	v_lshl_add_u64 v[110:111], v[116:117], 1, s[8:9]
	v_lshl_add_u64 v[74:75], v[108:109], 2, s[36:37]
	s_waitcnt vmcnt(1)
	v_pk_fma_f32 v[78:79], v[78:79], v[134:135], v[86:87]
	v_pk_fma_f32 v[76:77], v[76:77], v[132:133], v[84:85]
	s_waitcnt vmcnt(0)
	v_pk_fma_f32 v[84:85], v[100:101], v[130:131], v[94:95]
	v_pk_fma_f32 v[86:87], v[102:103], v[128:129], v[92:93]
	v_cvt_pk_bf16_f32 v76, v76, v77
	v_cvt_pk_bf16_f32 v77, v78, v79
	v_cvt_pk_bf16_f32 v78, v86, v87
	v_cvt_pk_bf16_f32 v79, v84, v85
	global_store_dwordx4 v[110:111], v[76:79], off
	global_load_dwordx4 v[76:79], v[74:75], off nt
	s_nop 0
	global_load_dwordx4 v[84:87], v[74:75], off offset:16 nt
	v_lshl_add_u64 v[92:93], v[108:109], 1, s[8:9]
	s_waitcnt vmcnt(1)
	v_pk_fma_f32 v[66:67], v[66:67], v[134:135], v[78:79]
	v_pk_fma_f32 v[64:65], v[64:65], v[132:133], v[76:77]
	s_waitcnt vmcnt(0)
	v_pk_fma_f32 v[76:77], v[58:59], v[130:131], v[86:87]
	v_pk_fma_f32 v[58:59], v[56:57], v[128:129], v[84:85]
	v_cvt_pk_bf16_f32 v56, v64, v65
	v_cvt_pk_bf16_f32 v57, v66, v67
	v_cvt_pk_bf16_f32 v58, v58, v59
	v_cvt_pk_bf16_f32 v59, v76, v77
	global_store_dwordx4 v[92:93], v[56:59], off
	global_load_dwordx4 v[76:79], v[160:161], off offset:512 nt
	global_load_dwordx4 v[64:67], v[158:159], off offset:512
	s_nop 0
	global_load_dwordx4 v[56:59], v[158:159], off offset:528
	global_load_dwordx4 v[84:87], v[160:161], off offset:528 nt
	v_pk_add_f32 v[92:93], v[60:61], 0 op_sel_hi:[1,0]
	v_or_b32_e32 v60, 0x80, v154
	v_ashrrev_i32_e32 v61, 31, v60
	v_lshl_add_u64 v[94:95], v[156:157], 0, v[60:61]
	v_lshl_add_u64 v[94:95], v[94:95], 1, s[8:9]
	s_waitcnt vmcnt(2)
;     __device__ __forceinline__ void operator()(const f32x4 (&acc)[2][2][4][2], const Unit& u, int wr, int wc, int fr, int fq) const {
;     ...
;         for (int bj = 0; bj < 2; ++bj) { const int c = col0 + bj * HALF;
;             const f32x4 g0 = *(const f32x4*)(gp + c), g1 = *(const f32x4*)(gp + c + 4);
;             const f32x4 b0 = bias ? *(const f32x4*)(bias + c) : (f32x4){0.f, 0.f, 0.f, 0.f}, b1 = bias ? *(const f32x4*)(bias + c + 4) : (f32x4){0.f, 0.f, 0.f, 0.f};
; #pragma unroll
;             for (int ai = 0; ai < 2; ++ai)
; #pragma unroll
;                 for (int m = 0; m < 4; ++m) { const size_t off = (size_t)(row0 + ai * HALF + m * 16) * 1024 + c;
;                     f32x4 x0, x1;
;                     if (BASE_BF16) { const u32x4 v = *(const u32x4*)((const bf16_t*)base + off);
;                         x0 = (f32x4){__uint_as_float(v.x << 16), __uint_as_float(v.x & 0xffff0000u), __uint_as_float(v.y << 16), __uint_as_float(v.y & 0xffff0000u)};
;                         x1 = (f32x4){__uint_as_float(v.z << 16), __uint_as_float(v.z & 0xffff0000u), __uint_as_float(v.w << 16), __uint_as_float(v.w & 0xffff0000u)}; }
;                     else { x0 = *(const f32x4*)((const float*)base + off); x1 = *(const f32x4*)((const float*)base + off + 4); }
;                     x0 = x0 + g0 * (acc[ai][bj][m][0] + b0); x1 = x1 + g1 * (acc[ai][bj][m][1] + b1);
;                     if (OUT_BF16) { u32x4 w; w.x = pk2(x0[0], x0[1]); w.y = pk2(x0[2], x0[3]); w.z = pk2(x1[0], x1[1]); w.w = pk2(x1[2], x1[3]); *(u32x4*)((bf16_t*)out + off) = w; }
;                     else { *(f32x4*)((float*)out + off) = x0; *(f32x4*)((float*)out + off + 4) = x1; } } }
; template <class Epi, class Sched, bool ALIGN_EPI = false, bool SP2 = false>
; __device__ __forceinline__ void gemm_phase(PG8_LAS unsigned char* lds, const Gemm g, const Sched& S, const Epi& E) {
;     ...
;         if constexpr (ALIGN_EPI) { if (wr == 0) PG8_BAR; }
;         if constexpr (!Epi::AFTER_DRAIN) { E(acc, cur, wr, wc, fr, fq); S.done(cur); }
;         if (!has_next) break;
; #pragma unroll
;         for (int a = 0; a < 2; ++a)
; #pragma unroll
;             for (int b = 0; b < 2; ++b)
; #pragma unroll
;                 for (int m = 0; m < 4; ++m)
; #pragma unroll
;                     for (int n = 0; n < 2; ++n) acc[a][b][m][n] = (f32x4){0.f, 0.f, 0.f, 0.f};
;         cur = nxt; cA = nA; cB = nB; ++ui;
	v_pk_fma_f32 v[70:71], v[70:71], v[66:67], v[78:79]
	v_pk_fma_f32 v[68:69], v[68:69], v[64:65], v[76:77]
	s_waitcnt vmcnt(0)
	v_pk_fma_f32 v[62:63], v[62:63], v[58:59], v[86:87]
	v_pk_fma_f32 v[76:77], v[92:93], v[56:57], v[84:85]
	v_cvt_pk_bf16_f32 v68, v68, v69
	v_cvt_pk_bf16_f32 v69, v70, v71
	v_cvt_pk_bf16_f32 v70, v76, v77
	v_cvt_pk_bf16_f32 v71, v62, v63
	global_store_dwordx4 v[94:95], v[68:71], off
	global_load_dwordx4 v[68:71], v[122:123], off offset:512 nt
	s_nop 0
	global_load_dwordx4 v[76:79], v[122:123], off offset:528 nt
	v_lshl_add_u64 v[62:63], v[120:121], 0, v[60:61]
	v_lshl_add_u64 v[62:63], v[62:63], 1, s[8:9]
	s_waitcnt vmcnt(1)
	v_pk_fma_f32 v[54:55], v[54:55], v[66:67], v[70:71]
	v_pk_fma_f32 v[52:53], v[52:53], v[64:65], v[68:69]
	s_waitcnt vmcnt(0)
	v_pk_fma_f32 v[68:69], v[50:51], v[58:59], v[78:79]
	v_pk_fma_f32 v[50:51], v[48:49], v[56:57], v[76:77]
	v_cvt_pk_bf16_f32 v48, v52, v53
	v_cvt_pk_bf16_f32 v49, v54, v55
	v_cvt_pk_bf16_f32 v50, v50, v51
	v_cvt_pk_bf16_f32 v51, v68, v69
	global_store_dwordx4 v[62:63], v[48:51], off
	global_load_dwordx4 v[48:51], v[114:115], off offset:512 nt
	s_nop 0
	global_load_dwordx4 v[52:55], v[114:115], off offset:528 nt
	v_lshl_add_u64 v[62:63], v[112:113], 0, v[60:61]
	v_lshl_add_u64 v[62:63], v[62:63], 1, s[8:9]
	s_waitcnt vmcnt(1)
	v_pk_fma_f32 v[46:47], v[46:47], v[66:67], v[50:51]
	v_pk_fma_f32 v[44:45], v[44:45], v[64:65], v[48:49]
	s_waitcnt vmcnt(0)
	v_pk_fma_f32 v[48:49], v[42:43], v[58:59], v[54:55]
	v_pk_fma_f32 v[42:43], v[40:41], v[56:57], v[52:53]
	v_cvt_pk_bf16_f32 v40, v44, v45
	v_cvt_pk_bf16_f32 v41, v46, v47
	v_cvt_pk_bf16_f32 v42, v42, v43
	v_cvt_pk_bf16_f32 v43, v48, v49
	global_store_dwordx4 v[62:63], v[40:43], off
	global_load_dwordx4 v[40:43], v[106:107], off offset:512 nt
	s_nop 0
	global_load_dwordx4 v[44:47], v[106:107], off offset:528 nt
	v_lshl_add_u64 v[48:49], v[104:105], 0, v[60:61]
	v_lshl_add_u64 v[48:49], v[48:49], 1, s[8:9]
	s_waitcnt vmcnt(1)
	v_pk_fma_f32 v[38:39], v[38:39], v[66:67], v[42:43]
	v_pk_fma_f32 v[36:37], v[36:37], v[64:65], v[40:41]
	s_waitcnt vmcnt(0)
	v_pk_fma_f32 v[40:41], v[34:35], v[58:59], v[46:47]
	v_pk_fma_f32 v[34:35], v[32:33], v[56:57], v[44:45]
	v_cvt_pk_bf16_f32 v32, v36, v37
	v_cvt_pk_bf16_f32 v33, v38, v39
	v_cvt_pk_bf16_f32 v34, v34, v35
	v_cvt_pk_bf16_f32 v35, v40, v41
	global_store_dwordx4 v[48:49], v[32:35], off
	global_load_dwordx4 v[32:35], v[98:99], off offset:512 nt
	s_nop 0
	global_load_dwordx4 v[36:39], v[98:99], off offset:528 nt
	v_lshl_add_u64 v[40:41], v[96:97], 0, v[60:61]
	v_lshl_add_u64 v[40:41], v[40:41], 1, s[8:9]
	s_waitcnt vmcnt(1)
	v_pk_fma_f32 v[30:31], v[30:31], v[66:67], v[34:35]
	v_pk_fma_f32 v[28:29], v[28:29], v[64:65], v[32:33]
	s_waitcnt vmcnt(0)
	v_pk_fma_f32 v[32:33], v[26:27], v[58:59], v[38:39]
	v_pk_fma_f32 v[26:27], v[24:25], v[56:57], v[36:37]
	v_cvt_pk_bf16_f32 v24, v28, v29
	v_cvt_pk_bf16_f32 v25, v30, v31
	v_cvt_pk_bf16_f32 v26, v26, v27
	v_cvt_pk_bf16_f32 v27, v32, v33
	global_store_dwordx4 v[40:41], v[24:27], off
	global_load_dwordx4 v[24:27], v[90:91], off offset:512 nt
	s_nop 0
	global_load_dwordx4 v[28:31], v[90:91], off offset:528 nt
	v_lshl_add_u64 v[32:33], v[88:89], 0, v[60:61]
	v_lshl_add_u64 v[32:33], v[32:33], 1, s[8:9]
	s_waitcnt vmcnt(1)
	v_pk_fma_f32 v[22:23], v[22:23], v[66:67], v[26:27]
	v_pk_fma_f32 v[20:21], v[20:21], v[64:65], v[24:25]
	s_waitcnt vmcnt(0)
	v_pk_fma_f32 v[24:25], v[18:19], v[58:59], v[30:31]
	v_pk_fma_f32 v[18:19], v[16:17], v[56:57], v[28:29]
	v_cvt_pk_bf16_f32 v16, v20, v21
	v_cvt_pk_bf16_f32 v17, v22, v23
	v_cvt_pk_bf16_f32 v18, v18, v19
	v_cvt_pk_bf16_f32 v19, v24, v25
	global_store_dwordx4 v[32:33], v[16:19], off
	global_load_dwordx4 v[16:19], v[82:83], off offset:512 nt
	s_nop 0
	global_load_dwordx4 v[20:23], v[82:83], off offset:528 nt
	v_lshl_add_u64 v[24:25], v[80:81], 0, v[60:61]
	v_lshl_add_u64 v[24:25], v[24:25], 1, s[8:9]
	s_waitcnt vmcnt(1)
	v_pk_fma_f32 v[14:15], v[14:15], v[66:67], v[18:19]
	v_pk_fma_f32 v[12:13], v[12:13], v[64:65], v[16:17]
	s_waitcnt vmcnt(0)
	v_pk_fma_f32 v[16:17], v[10:11], v[58:59], v[22:23]
	v_pk_fma_f32 v[10:11], v[8:9], v[56:57], v[20:21]
	v_cvt_pk_bf16_f32 v8, v12, v13
	v_cvt_pk_bf16_f32 v9, v14, v15
	v_cvt_pk_bf16_f32 v10, v10, v11
	v_cvt_pk_bf16_f32 v11, v16, v17
	global_store_dwordx4 v[24:25], v[8:11], off
	global_load_dwordx4 v[8:11], v[74:75], off offset:512 nt
	s_nop 0
	global_load_dwordx4 v[12:15], v[74:75], off offset:528 nt
	v_lshl_add_u64 v[16:17], v[72:73], 0, v[60:61]
	v_lshl_add_u64 v[16:17], v[16:17], 1, s[8:9]
	s_waitcnt vmcnt(1)
	v_pk_fma_f32 v[6:7], v[6:7], v[66:67], v[10:11]
	v_pk_fma_f32 v[4:5], v[4:5], v[64:65], v[8:9]
	s_waitcnt vmcnt(0)
	v_pk_fma_f32 v[8:9], v[2:3], v[58:59], v[14:15]
	v_pk_fma_f32 v[2:3], v[0:1], v[56:57], v[12:13]
	v_cvt_pk_bf16_f32 v0, v4, v5
	v_cvt_pk_bf16_f32 v1, v6, v7
	v_cvt_pk_bf16_f32 v2, v2, v3
	v_cvt_pk_bf16_f32 v3, v8, v9
	global_store_dwordx4 v[16:17], v[0:3], off
	s_cbranch_vccnz .LBB0_582
	s_andn2_b64 vcc, exec, s[6:7]
	s_cbranch_vccnz .LBB0_581
	s_barrier
	s_branch .LBB0_581

; #define LAS __attribute__((address_space(3)))
; #define TP_LOAD(item_) do { const int c0_ = ((item_) & 15) * 64, t0_ = ((item_) >> 4) * 64; \
;         _Pragma("unroll") for (int j = 0; j < 8; ++j) nx[j] = *(const u32x4*)(Gc + (size_t)(c0_ + 8 * j + (lane >> 3)) * GLD + t0_ + 8 * (lane & 7)); } while (0)
; __device__ __forceinline__ void transpose_phase(LAS unsigned char* L, const Args& a) {
;     const int tid = threadIdx.x, lane = tid & 63, w = tid >> 6; const int gw = blockIdx.x * 8 + w, NGW = gridDim.x * 8;
;     const bf16_t* Gc = (const bf16_t*)(a.ws + WS_G); bf16_t* GT = (bf16_t*)(a.ws + WS_GT);
;     LAS unsigned char* T = L + w * 16384;
;     u32x4 nx[8];
;     ...
;     if (gw < 16 * 1024) TP_LOAD(gw);
.LBB0_1137:
	s_cmp_lt_i32 s30, 13
	s_cselect_b64 s[4:5], -1, 0
	s_and_b64 s[4:5], s[4:5], s[0:1]
	s_andn2_b64 vcc, exec, s[4:5]
	s_cbranch_vccnz .LBB0_1146
	v_lshl_add_u32 v38, s2, 3, v228
	s_movk_i32 s0, 0x4000
	v_cmp_gt_i32_e32 vcc, s0, v38
	s_and_saveexec_b64 s[6:7], vcc
	s_cbranch_execz .LBB0_1145
	v_lshlrev_b32_e32 v0, 3, v152
	s_lshl_b32 s12, s3, 3
	v_and_b32_e32 v44, 56, v0
	v_lshlrev_b32_e32 v0, 2, v38
	s_add_u32 s0, s28, 0x27a00000
	v_and_b32_e32 v0, 0xffffffc0, v0
	s_addc_u32 s1, s29, 0
	v_bfe_u32 v39, v152, 3, 3
	v_ashrrev_i32_e32 v1, 31, v0
	v_lshlrev_b32_e32 v2, 6, v38
	s_movk_i32 s13, 0x3c0
	v_lshlrev_b32_e32 v32, 1, v44
	v_mov_b32_e32 v33, 0
	v_lshl_add_u64 v[0:1], v[0:1], 1, s[0:1]
	v_and_or_b32 v2, v2, s13, v39
	v_lshl_add_u64 v[34:35], s[0:1], 0, v[32:33]
	v_lshl_add_u64 v[36:37], s[16:17], 0, v[32:33]
	v_lshl_add_u64 v[0:1], v[0:1], 0, v[32:33]
	v_lshlrev_b32_e32 v32, 17, v2
	v_lshl_add_u64 v[24:25], v[0:1], 0, v[32:33]
	s_mov_b32 s0, 0x100000
	v_add_co_u32_e32 v8, vcc, s0, v24
	s_mov_b32 s0, 0x200000
	s_nop 0
	v_addc_co_u32_e32 v9, vcc, 0, v25, vcc
	v_add_co_u32_e32 v16, vcc, s0, v24
	s_mov_b32 s0, 0x300000
	s_nop 0
	v_addc_co_u32_e32 v17, vcc, 0, v25, vcc
	v_add_co_u32_e32 v18, vcc, s0, v24
	s_mov_b32 s0, 0x400000
	s_nop 0
	v_addc_co_u32_e32 v19, vcc, 0, v25, vcc
	v_add_co_u32_e32 v26, vcc, s0, v24
	s_mov_b32 s0, 0x500000
	s_nop 0
	v_addc_co_u32_e32 v27, vcc, 0, v25, vcc
	v_add_co_u32_e32 v28, vcc, s0, v24
	s_mov_b32 s0, 0x600000
	s_nop 0
	v_addc_co_u32_e32 v29, vcc, 0, v25, vcc
	v_add_co_u32_e32 v40, vcc, s0, v24
	s_mov_b32 s0, 0x700000
	s_nop 0
	v_addc_co_u32_e32 v41, vcc, 0, v25, vcc
	v_add_co_u32_e32 v42, vcc, s0, v24
	global_load_dwordx4 v[0:3], v[24:25], off nt
	global_load_dwordx4 v[4:7], v[8:9], off nt
	s_nop 0
	global_load_dwordx4 v[8:11], v[16:17], off nt
	global_load_dwordx4 v[12:15], v[18:19], off nt
	s_nop 0
	global_load_dwordx4 v[16:19], v[26:27], off nt
	s_waitcnt lgkmcnt(0)
	global_load_dwordx4 v[20:23], v[28:29], off nt
	v_addc_co_u32_e32 v43, vcc, 0, v25, vcc
	global_load_dwordx4 v[24:27], v[40:41], off nt
	global_load_dwordx4 v[28:31], v[42:43], off nt
	v_lshlrev_b32_e32 v40, 4, v152
	v_lshl_add_u32 v32, v228, 14, 0
	v_and_b32_e32 v40, 0x70, v40
	s_movk_i32 s0, 0x84
	s_waitcnt vmcnt(0)
	v_add_u32_e32 v47, v32, v40
	v_mad_u32_u24 v32, v44, s0, v32
	v_or_b32_e32 v40, 8, v39
	v_or_b32_e32 v41, 16, v39
	v_or_b32_e32 v42, 24, v39
	v_or_b32_e32 v43, 32, v39
	v_or_b32_e32 v44, 40, v39
	v_or_b32_e32 v45, 48, v39
	v_or_b32_e32 v46, 56, v39
	v_lshlrev_b32_e32 v57, 6, v228
	v_lshlrev_b32_e32 v48, 1, v39
	v_mul_u32_u24_e32 v49, 0x84, v39
	v_lshlrev_b32_e32 v50, 1, v40
	v_lshlrev_b32_e32 v51, 1, v41
	v_lshlrev_b32_e32 v52, 1, v42
	v_lshlrev_b32_e32 v53, 1, v43
	v_lshlrev_b32_e32 v54, 1, v44
	v_lshlrev_b32_e32 v55, 1, v45
	v_lshlrev_b32_e32 v56, 1, v46
	v_lshl_add_u32 v58, s2, 9, v57
	v_lshlrev_b32_e32 v57, 2, v228
	s_lshl_b32 s14, s3, 9
	s_lshl_b32 s15, s3, 5
	v_lshl_add_u32 v59, s2, 5, v57
	s_mov_b64 s[8:9], 0
	v_add_u32_e32 v47, v47, v49
	s_movk_i32 s20, 0x3fff
	v_add_u32_e32 v48, v32, v48
	v_add_u32_e32 v49, v32, v50
	v_add_u32_e32 v50, v32, v51
	v_add_u32_e32 v51, v32, v52
	v_add_u32_e32 v52, v32, v53
	v_add_u32_e32 v53, v32, v54
	v_add_u32_e32 v54, v32, v55
	v_add_u32_e32 v55, v32, v56
	s_branch .LBB0_1141

; #define LAS __attribute__((address_space(3)))
; #define TP_LOAD(item_) do { const int c0_ = ((item_) & 15) * 64, t0_ = ((item_) >> 4) * 64; \
;         _Pragma("unroll") for (int j = 0; j < 8; ++j) nx[j] = *(const u32x4*)(Gc + (size_t)(c0_ + 8 * j + (lane >> 3)) * GLD + t0_ + 8 * (lane & 7)); } while (0)
; __device__ __forceinline__ void transpose_phase(LAS unsigned char* L, const Args& a) {
;     ...
;     for (int item = gw; item < 16 * 1024; item += NGW) {
;         const int cblk = item & 15, tblk = item >> 4; const int c0 = cblk * 64, t0 = tblk * 64;
; #pragma unroll
;         for (int j = 0; j < 8; ++j) { const int c = 8 * j + (lane >> 3), ch = lane & 7; const u32x4 v = nx[j];
;             LAS unsigned* d = (LAS unsigned*)(T + c * 132 + ch * 16); d[0] = v.x; d[1] = v.y; d[2] = v.z; d[3] = v.w; }
;         if (item + NGW < 16 * 1024) TP_LOAD(item + NGW);
.LBB0_1141:
	v_add_u32_e32 v32, 0x420, v47
	s_waitcnt vmcnt(15)
	ds_write2_b32 v47, v0, v1 offset1:1
	ds_write2_b32 v47, v2, v3 offset0:2 offset1:3
	s_waitcnt vmcnt(14)
	ds_write2_b32 v32, v4, v5 offset1:1
	v_add_u32_e32 v32, 0x428, v47
	ds_write2_b32 v32, v6, v7 offset1:1
	v_add_u32_e32 v32, 0x840, v47
	s_waitcnt vmcnt(13)
	ds_write2_b32 v32, v8, v9 offset1:1
	v_add_u32_e32 v32, 0x848, v47
	ds_write2_b32 v32, v10, v11 offset1:1
	v_add_u32_e32 v32, 0xc60, v47
	s_waitcnt vmcnt(12)
	ds_write2_b32 v32, v12, v13 offset1:1
	v_add_u32_e32 v32, 0xc68, v47
	ds_write2_b32 v32, v14, v15 offset1:1
	v_add_u32_e32 v32, 0x1080, v47
	s_waitcnt vmcnt(11)
	ds_write2_b32 v32, v16, v17 offset1:1
	v_add_u32_e32 v32, 0x1088, v47
	ds_write2_b32 v32, v18, v19 offset1:1
	v_add_u32_e32 v32, 0x14a0, v47
	s_waitcnt vmcnt(10)
	ds_write2_b32 v32, v20, v21 offset1:1
	v_add_u32_e32 v32, 0x14a8, v47
	ds_write2_b32 v32, v22, v23 offset1:1
	v_add_u32_e32 v32, 0x18c0, v47
	s_waitcnt vmcnt(9)
	ds_write2_b32 v32, v24, v25 offset1:1
	v_add_u32_e32 v32, 0x18c8, v47
	ds_write2_b32 v32, v26, v27 offset1:1
	v_add_u32_e32 v32, 0x1ce0, v47
	v_add_u32_e32 v38, s12, v38
	s_waitcnt vmcnt(8)
	ds_write2_b32 v32, v28, v29 offset1:1
	v_add_u32_e32 v32, 0x1ce8, v47
	v_cmp_lt_i32_e64 s[0:1], s20, v38
	ds_write2_b32 v32, v30, v31 offset1:1
	s_and_saveexec_b64 s[10:11], s[0:1]
	s_xor_b64 s[10:11], exec, s[10:11]
	v_add_u32_e32 v56, s14, v58
	v_add_u32_e32 v57, s15, v59
	s_andn2_saveexec_b64 s[10:11], s[10:11]
	s_cbranch_execz .LBB0_1140
	v_add_u32_e32 v57, s15, v59
	v_add_u32_e32 v56, s14, v58
	v_and_b32_e32 v0, 0xffffffc0, v57
	v_and_or_b32 v2, v56, s13, v39
	v_ashrrev_i32_e32 v1, 31, v0
	v_lshl_add_u64 v[0:1], v[0:1], 1, v[34:35]
	v_lshlrev_b32_e32 v32, 17, v2
	v_lshl_add_u64 v[24:25], v[0:1], 0, v[32:33]
	v_add_co_u32_e32 v8, vcc, 0x100000, v24
	s_nop 1
	v_addc_co_u32_e32 v9, vcc, 0, v25, vcc
	v_add_co_u32_e32 v16, vcc, 0x200000, v24
	global_load_dwordx4 v[0:3], v[24:25], off nt
	global_load_dwordx4 v[4:7], v[8:9], off nt
	v_addc_co_u32_e32 v17, vcc, 0, v25, vcc
	v_add_co_u32_e32 v18, vcc, 0x300000, v24
	s_nop 1
	v_addc_co_u32_e32 v19, vcc, 0, v25, vcc
	v_add_co_u32_e32 v26, vcc, 0x400000, v24
	global_load_dwordx4 v[8:11], v[16:17], off nt
	global_load_dwordx4 v[12:15], v[18:19], off nt
	v_addc_co_u32_e32 v27, vcc, 0, v25, vcc
	v_add_co_u32_e32 v28, vcc, 0x500000, v24
	s_nop 1
	v_addc_co_u32_e32 v29, vcc, 0, v25, vcc
	v_add_co_u32_e32 v60, vcc, 0x600000, v24
	global_load_dwordx4 v[16:19], v[26:27], off nt
	global_load_dwordx4 v[20:23], v[28:29], off nt
	v_addc_co_u32_e32 v61, vcc, 0, v25, vcc
	v_add_co_u32_e32 v62, vcc, 0x700000, v24
	s_nop 1
	v_addc_co_u32_e32 v63, vcc, 0, v25, vcc
	global_load_dwordx4 v[24:27], v[60:61], off nt
	global_load_dwordx4 v[28:31], v[62:63], off nt
	s_branch .LBB0_1140

; __device__ __forceinline__ unsigned pk2(float lo, float hi) { f32x2 v = {lo, hi}; bf16x2_t b = __builtin_convertvector(v, bf16x2_t); return __builtin_bit_cast(unsigned, b); }
;     __device__ __forceinline__ void operator()(const f32x4 (&acc)[2][2][4][2], const Unit& u, int wr, int wc, int fr, int fq) const {
;     ...
;         for (int bj = 0; bj < 2; ++bj) { const int c = col0 + bj * HALF;
;             const f32x4 g0 = *(const f32x4*)(gp + c), g1 = *(const f32x4*)(gp + c + 4);
;             const f32x4 b0 = bias ? *(const f32x4*)(bias + c) : (f32x4){0.f, 0.f, 0.f, 0.f}, b1 = bias ? *(const f32x4*)(bias + c + 4) : (f32x4){0.f, 0.f, 0.f, 0.f};
; #pragma unroll
;             for (int ai = 0; ai < 2; ++ai)
; #pragma unroll
;                 for (int m = 0; m < 4; ++m) { const size_t off = (size_t)(row0 + ai * HALF + m * 16) * 1024 + c;
;                     f32x4 x0, x1;
;                     if (BASE_BF16) { const u32x4 v = *(const u32x4*)((const bf16_t*)base + off);
;                         x0 = (f32x4){__uint_as_float(v.x << 16), __uint_as_float(v.x & 0xffff0000u), __uint_as_float(v.y << 16), __uint_as_float(v.y & 0xffff0000u)};
;                         x1 = (f32x4){__uint_as_float(v.z << 16), __uint_as_float(v.z & 0xffff0000u), __uint_as_float(v.w << 16), __uint_as_float(v.w & 0xffff0000u)}; }
;                     else { x0 = *(const f32x4*)((const float*)base + off); x1 = *(const f32x4*)((const float*)base + off + 4); }
;                     x0 = x0 + g0 * (acc[ai][bj][m][0] + b0); x1 = x1 + g1 * (acc[ai][bj][m][1] + b1);
;                     if (OUT_BF16) { u32x4 w; w.x = pk2(x0[0], x0[1]); w.y = pk2(x0[2], x0[3]); w.z = pk2(x1[0], x1[1]); w.w = pk2(x1[2], x1[3]); *(u32x4*)((bf16_t*)out + off) = w; }
;                     else { *(f32x4*)((float*)out + off) = x0; *(f32x4*)((float*)out + off + 4) = x1; } } }
.LBB0_1420:
	v_lshl_add_u32 v168, s53, 8, v158
	v_lshl_or_b32 v152, s54, 8, v160
	v_ashrrev_i32_e32 v169, 31, v168
	v_lshlrev_b64 v[156:157], 10, v[168:169]
	v_ashrrev_i32_e32 v153, 31, v152
	s_ashr_i32 s24, s53, 5
	v_lshl_add_u64 v[170:171], v[156:157], 0, v[152:153]
	s_mul_hi_i32 s25, s24, 0x6000
	s_mulk_i32 s24, 0x6000
	v_lshl_add_u64 v[128:129], v[170:171], 1, s[8:9]
	s_add_u32 s24, s44, s24
	global_load_dwordx4 v[164:167], v[128:129], off
	s_addc_u32 s25, s45, s25
	v_lshl_add_u64 v[154:155], v[152:153], 2, s[24:25]
	global_load_dwordx4 v[132:135], v[154:155], off
	global_load_dwordx4 v[128:131], v[154:155], off offset:16
	v_pk_add_f32 v[174:175], v[120:121], 0 op_sel_hi:[1,0]
	v_or_b32_e32 v120, 16, v168
	v_ashrrev_i32_e32 v121, 31, v120
	v_pk_add_f32 v[126:127], v[126:127], 0 op_sel_hi:[1,0]
	v_pk_add_f32 v[124:125], v[124:125], 0 op_sel_hi:[1,0]
	v_pk_add_f32 v[172:173], v[122:123], 0 op_sel_hi:[1,0]
	v_lshlrev_b64 v[122:123], 10, v[120:121]
	v_lshl_add_u64 v[120:121], v[170:171], 2, s[26:27]
	v_lshl_add_u64 v[170:171], v[122:123], 0, v[152:153]
	v_lshl_add_u64 v[176:177], v[170:171], 1, s[8:9]
	v_pk_add_f32 v[118:119], v[118:119], 0 op_sel_hi:[1,0]
	v_pk_add_f32 v[116:117], v[116:117], 0 op_sel_hi:[1,0]
	v_pk_add_f32 v[110:111], v[110:111], 0 op_sel_hi:[1,0]
	v_pk_add_f32 v[108:109], v[108:109], 0 op_sel_hi:[1,0]
	v_pk_add_f32 v[102:103], v[102:103], 0 op_sel_hi:[1,0]
	v_pk_add_f32 v[100:101], v[100:101], 0 op_sel_hi:[1,0]
	v_pk_add_f32 v[94:95], v[94:95], 0 op_sel_hi:[1,0]
	v_pk_add_f32 v[92:93], v[92:93], 0 op_sel_hi:[1,0]
	v_pk_add_f32 v[86:87], v[86:87], 0 op_sel_hi:[1,0]
	v_pk_add_f32 v[84:85], v[84:85], 0 op_sel_hi:[1,0]
	v_pk_add_f32 v[78:79], v[78:79], 0 op_sel_hi:[1,0]
	v_pk_add_f32 v[74:75], v[74:75], 0 op_sel_hi:[1,0]
	v_pk_add_f32 v[70:71], v[70:71], 0 op_sel_hi:[1,0]
	v_pk_add_f32 v[68:69], v[68:69], 0 op_sel_hi:[1,0]
	v_pk_add_f32 v[66:67], v[66:67], 0 op_sel_hi:[1,0]
	v_pk_add_f32 v[64:65], v[64:65], 0 op_sel_hi:[1,0]
	v_pk_add_f32 v[54:55], v[54:55], 0 op_sel_hi:[1,0]
	v_pk_add_f32 v[52:53], v[52:53], 0 op_sel_hi:[1,0]
	v_pk_add_f32 v[46:47], v[46:47], 0 op_sel_hi:[1,0]
	v_pk_add_f32 v[44:45], v[44:45], 0 op_sel_hi:[1,0]
	v_pk_add_f32 v[38:39], v[38:39], 0 op_sel_hi:[1,0]
	v_pk_add_f32 v[36:37], v[36:37], 0 op_sel_hi:[1,0]
	v_pk_add_f32 v[30:31], v[30:31], 0 op_sel_hi:[1,0]
	v_pk_add_f32 v[28:29], v[28:29], 0 op_sel_hi:[1,0]
	v_pk_add_f32 v[22:23], v[22:23], 0 op_sel_hi:[1,0]
	v_pk_add_f32 v[20:21], v[20:21], 0 op_sel_hi:[1,0]
	v_pk_add_f32 v[14:15], v[14:15], 0 op_sel_hi:[1,0]
	v_pk_add_f32 v[12:13], v[12:13], 0 op_sel_hi:[1,0]
	v_pk_add_f32 v[6:7], v[6:7], 0 op_sel_hi:[1,0]
	v_pk_add_f32 v[4:5], v[4:5], 0 op_sel_hi:[1,0]
	s_and_b64 vcc, exec, s[0:1]
	s_mov_b64 s[0:1], -1
	s_waitcnt vmcnt(0)
	v_lshlrev_b32_e32 v178, 16, v164
	v_and_b32_e32 v179, 0xffff0000, v164
	v_lshlrev_b32_e32 v164, 16, v165
	v_and_b32_e32 v165, 0xffff0000, v165
	v_lshlrev_b32_e32 v180, 16, v166
	v_and_b32_e32 v181, 0xffff0000, v166
	v_lshlrev_b32_e32 v166, 16, v167
	v_and_b32_e32 v167, 0xffff0000, v167
	v_pk_fma_f32 v[126:127], v[126:127], v[134:135], v[164:165]
	v_pk_fma_f32 v[124:125], v[124:125], v[132:133], v[178:179]
	v_pk_fma_f32 v[166:167], v[172:173], v[130:131], v[166:167]
	v_pk_fma_f32 v[164:165], v[174:175], v[128:129], v[180:181]
	global_store_dwordx4 v[120:121], v[124:127], off nt
	global_store_dwordx4 v[120:121], v[164:167], off offset:16 nt
	global_load_dwordx4 v[124:127], v[176:177], off
	s_waitcnt vmcnt(0)
	v_lshlrev_b32_e32 v174, 16, v124
	v_pk_add_f32 v[166:167], v[112:113], 0 op_sel_hi:[1,0]
	v_or_b32_e32 v112, 32, v168
	v_ashrrev_i32_e32 v113, 31, v112
	v_pk_add_f32 v[164:165], v[114:115], 0 op_sel_hi:[1,0]
	v_lshlrev_b64 v[114:115], 10, v[112:113]
	v_and_b32_e32 v175, 0xffff0000, v124
	v_lshlrev_b32_e32 v124, 16, v125
	v_and_b32_e32 v125, 0xffff0000, v125
	v_lshl_add_u64 v[172:173], v[114:115], 0, v[152:153]
	v_lshl_add_u64 v[112:113], v[170:171], 2, s[26:27]
	v_lshlrev_b32_e32 v176, 16, v126
	v_and_b32_e32 v177, 0xffff0000, v126
	v_lshlrev_b32_e32 v126, 16, v127
	v_and_b32_e32 v127, 0xffff0000, v127
	v_pk_fma_f32 v[118:119], v[118:119], v[134:135], v[124:125]
	v_pk_fma_f32 v[116:117], v[116:117], v[132:133], v[174:175]
	v_lshl_add_u64 v[170:171], v[172:173], 1, s[8:9]
	v_pk_fma_f32 v[126:127], v[164:165], v[130:131], v[126:127]
	v_pk_fma_f32 v[124:125], v[166:167], v[128:129], v[176:177]
	global_store_dwordx4 v[112:113], v[116:119], off nt
	global_store_dwordx4 v[112:113], v[124:127], off offset:16 nt
	global_load_dwordx4 v[116:119], v[170:171], off
	s_waitcnt vmcnt(0)
	v_and_b32_e32 v169, 0xffff0000, v116
	v_pk_add_f32 v[126:127], v[104:105], 0 op_sel_hi:[1,0]
	v_or_b32_e32 v104, 48, v168
	v_ashrrev_i32_e32 v105, 31, v104
	v_pk_add_f32 v[124:125], v[106:107], 0 op_sel_hi:[1,0]
	v_lshlrev_b64 v[106:107], 10, v[104:105]
	v_lshlrev_b32_e32 v168, 16, v116
	v_lshlrev_b32_e32 v116, 16, v117
	v_and_b32_e32 v117, 0xffff0000, v117
	v_lshl_add_u64 v[164:165], v[106:107], 0, v[152:153]
	v_lshl_add_u64 v[104:105], v[172:173], 2, s[26:27]
	v_lshlrev_b32_e32 v170, 16, v118
	v_and_b32_e32 v171, 0xffff0000, v118
	v_lshlrev_b32_e32 v118, 16, v119
	v_and_b32_e32 v119, 0xffff0000, v119
	v_pk_fma_f32 v[110:111], v[110:111], v[134:135], v[116:117]
	v_pk_fma_f32 v[108:109], v[108:109], v[132:133], v[168:169]
	v_lshl_add_u64 v[166:167], v[164:165], 1, s[8:9]
	v_pk_fma_f32 v[118:119], v[124:125], v[130:131], v[118:119]
	v_pk_fma_f32 v[116:117], v[126:127], v[128:129], v[170:171]
	global_store_dwordx4 v[104:105], v[108:111], off nt
	global_store_dwordx4 v[104:105], v[116:119], off offset:16 nt
	global_load_dwordx4 v[108:111], v[166:167], off
	s_waitcnt vmcnt(0)
; __device__ __forceinline__ unsigned pk2(float lo, float hi) { f32x2 v = {lo, hi}; bf16x2_t b = __builtin_convertvector(v, bf16x2_t); return __builtin_bit_cast(unsigned, b); }
;     __device__ __forceinline__ void operator()(const f32x4 (&acc)[2][2][4][2], const Unit& u, int wr, int wc, int fr, int fq) const {
;     ...
;         for (int bj = 0; bj < 2; ++bj) { const int c = col0 + bj * HALF;
;             const f32x4 g0 = *(const f32x4*)(gp + c), g1 = *(const f32x4*)(gp + c + 4);
;             const f32x4 b0 = bias ? *(const f32x4*)(bias + c) : (f32x4){0.f, 0.f, 0.f, 0.f}, b1 = bias ? *(const f32x4*)(bias + c + 4) : (f32x4){0.f, 0.f, 0.f, 0.f};
; #pragma unroll
;             for (int ai = 0; ai < 2; ++ai)
; #pragma unroll
;                 for (int m = 0; m < 4; ++m) { const size_t off = (size_t)(row0 + ai * HALF + m * 16) * 1024 + c;
;                     f32x4 x0, x1;
;                     if (BASE_BF16) { const u32x4 v = *(const u32x4*)((const bf16_t*)base + off);
;                         x0 = (f32x4){__uint_as_float(v.x << 16), __uint_as_float(v.x & 0xffff0000u), __uint_as_float(v.y << 16), __uint_as_float(v.y & 0xffff0000u)};
;                         x1 = (f32x4){__uint_as_float(v.z << 16), __uint_as_float(v.z & 0xffff0000u), __uint_as_float(v.w << 16), __uint_as_float(v.w & 0xffff0000u)}; }
;                     else { x0 = *(const f32x4*)((const float*)base + off); x1 = *(const f32x4*)((const float*)base + off + 4); }
;                     x0 = x0 + g0 * (acc[ai][bj][m][0] + b0); x1 = x1 + g1 * (acc[ai][bj][m][1] + b1);
;                     if (OUT_BF16) { u32x4 w; w.x = pk2(x0[0], x0[1]); w.y = pk2(x0[2], x0[3]); w.z = pk2(x1[0], x1[1]); w.w = pk2(x1[2], x1[3]); *(u32x4*)((bf16_t*)out + off) = w; }
;                     else { *(f32x4*)((float*)out + off) = x0; *(f32x4*)((float*)out + off + 4) = x1; } } }
	v_lshlrev_b32_e32 v166, 16, v110
	v_pk_add_f32 v[116:117], v[98:99], 0 op_sel_hi:[1,0]
	v_pk_add_f32 v[118:119], v[96:97], 0 op_sel_hi:[1,0]
	v_lshl_add_u64 v[96:97], v[156:157], 0, s[14:15]
	v_lshl_add_u64 v[98:99], v[164:165], 2, s[26:27]
	v_lshlrev_b32_e32 v164, 16, v108
	v_and_b32_e32 v165, 0xffff0000, v108
	v_lshlrev_b32_e32 v108, 16, v109
	v_and_b32_e32 v109, 0xffff0000, v109
	v_lshl_add_u64 v[124:125], v[96:97], 0, v[152:153]
	v_and_b32_e32 v167, 0xffff0000, v110
	v_lshlrev_b32_e32 v110, 16, v111
	v_and_b32_e32 v111, 0xffff0000, v111
	v_pk_fma_f32 v[102:103], v[102:103], v[134:135], v[108:109]
	v_pk_fma_f32 v[100:101], v[100:101], v[132:133], v[164:165]
	v_lshl_add_u64 v[126:127], v[124:125], 1, s[8:9]
	v_pk_fma_f32 v[110:111], v[116:117], v[130:131], v[110:111]
	v_pk_fma_f32 v[108:109], v[118:119], v[128:129], v[166:167]
	global_store_dwordx4 v[98:99], v[100:103], off nt
	global_store_dwordx4 v[98:99], v[108:111], off offset:16 nt
	global_load_dwordx4 v[100:103], v[126:127], off
	s_waitcnt vmcnt(0)
	v_lshlrev_b32_e32 v126, 16, v102
	v_pk_add_f32 v[108:109], v[90:91], 0 op_sel_hi:[1,0]
	v_pk_add_f32 v[110:111], v[88:89], 0 op_sel_hi:[1,0]
	v_lshl_add_u64 v[90:91], v[156:157], 0, s[16:17]
	v_lshl_add_u64 v[88:89], v[124:125], 2, s[26:27]
	v_lshlrev_b32_e32 v124, 16, v100
	v_and_b32_e32 v125, 0xffff0000, v100
	v_lshlrev_b32_e32 v100, 16, v101
	v_and_b32_e32 v101, 0xffff0000, v101
	v_lshl_add_u64 v[116:117], v[90:91], 0, v[152:153]
	v_and_b32_e32 v127, 0xffff0000, v102
	v_lshlrev_b32_e32 v102, 16, v103
	v_and_b32_e32 v103, 0xffff0000, v103
	v_pk_fma_f32 v[94:95], v[94:95], v[134:135], v[100:101]
	v_pk_fma_f32 v[92:93], v[92:93], v[132:133], v[124:125]
	v_lshl_add_u64 v[118:119], v[116:117], 1, s[8:9]
	v_pk_fma_f32 v[102:103], v[108:109], v[130:131], v[102:103]
	v_pk_fma_f32 v[100:101], v[110:111], v[128:129], v[126:127]
	global_store_dwordx4 v[88:89], v[92:95], off nt
	global_store_dwordx4 v[88:89], v[100:103], off offset:16 nt
	global_load_dwordx4 v[92:95], v[118:119], off
	s_waitcnt vmcnt(0)
	v_lshlrev_b32_e32 v118, 16, v94
	v_pk_add_f32 v[100:101], v[82:83], 0 op_sel_hi:[1,0]
	v_pk_add_f32 v[102:103], v[80:81], 0 op_sel_hi:[1,0]
	v_lshl_add_u64 v[82:83], v[156:157], 0, s[18:19]
	v_lshl_add_u64 v[80:81], v[116:117], 2, s[26:27]
	v_lshlrev_b32_e32 v116, 16, v92
	v_and_b32_e32 v117, 0xffff0000, v92
	v_lshlrev_b32_e32 v92, 16, v93
	v_and_b32_e32 v93, 0xffff0000, v93
	v_lshl_add_u64 v[108:109], v[82:83], 0, v[152:153]
	v_and_b32_e32 v119, 0xffff0000, v94
	v_lshlrev_b32_e32 v94, 16, v95
	v_and_b32_e32 v95, 0xffff0000, v95
	v_pk_fma_f32 v[86:87], v[86:87], v[134:135], v[92:93]
	v_pk_fma_f32 v[84:85], v[84:85], v[132:133], v[116:117]
	v_lshl_add_u64 v[110:111], v[108:109], 1, s[8:9]
	v_pk_fma_f32 v[94:95], v[100:101], v[130:131], v[94:95]
	v_pk_fma_f32 v[92:93], v[102:103], v[128:129], v[118:119]
	global_store_dwordx4 v[80:81], v[84:87], off nt
	global_store_dwordx4 v[80:81], v[92:95], off offset:16 nt
	global_load_dwordx4 v[84:87], v[110:111], off
	v_pk_add_f32 v[100:101], v[72:73], 0 op_sel_hi:[1,0]
	v_pk_add_f32 v[92:93], v[76:77], 0 op_sel_hi:[1,0]
	v_lshl_add_u64 v[76:77], v[156:157], 0, s[20:21]
	v_lshl_add_u64 v[102:103], v[76:77], 0, v[152:153]
	v_lshl_add_u64 v[72:73], v[108:109], 2, s[26:27]
	v_lshl_add_u64 v[108:109], v[102:103], 1, s[8:9]
	s_waitcnt vmcnt(0)
	v_lshlrev_b32_e32 v94, 16, v84
	v_and_b32_e32 v95, 0xffff0000, v84
	v_lshlrev_b32_e32 v84, 16, v85
	v_and_b32_e32 v85, 0xffff0000, v85
	v_lshlrev_b32_e32 v110, 16, v86
	v_and_b32_e32 v111, 0xffff0000, v86
	v_lshlrev_b32_e32 v116, 16, v87
	v_and_b32_e32 v117, 0xffff0000, v87
	v_pk_fma_f32 v[86:87], v[78:79], v[134:135], v[84:85]
	v_pk_fma_f32 v[84:85], v[92:93], v[132:133], v[94:95]
	v_pk_fma_f32 v[94:95], v[74:75], v[130:131], v[116:117]
	v_pk_fma_f32 v[92:93], v[100:101], v[128:129], v[110:111]
	global_store_dwordx4 v[72:73], v[84:87], off nt
	global_store_dwordx4 v[72:73], v[92:95], off offset:16 nt
	global_load_dwordx4 v[84:87], v[108:109], off
	v_or_b32_e32 v78, 0x80, v152
	v_ashrrev_i32_e32 v79, 31, v78
	v_pk_add_f32 v[94:95], v[60:61], 0 op_sel_hi:[1,0]
	v_lshl_add_u64 v[60:61], v[156:157], 0, v[78:79]
	v_pk_add_f32 v[92:93], v[62:63], 0 op_sel_hi:[1,0]
	v_lshl_add_u64 v[100:101], v[60:61], 1, s[8:9]
	v_lshl_add_u64 v[74:75], v[102:103], 2, s[26:27]
	s_waitcnt vmcnt(0)
	v_lshlrev_b32_e32 v60, 16, v84
	v_and_b32_e32 v61, 0xffff0000, v84
	v_lshlrev_b32_e32 v62, 16, v85
	v_and_b32_e32 v63, 0xffff0000, v85
	v_lshlrev_b32_e32 v84, 16, v86
	v_and_b32_e32 v85, 0xffff0000, v86
	v_lshlrev_b32_e32 v86, 16, v87
	v_and_b32_e32 v87, 0xffff0000, v87
	v_pk_fma_f32 v[62:63], v[70:71], v[134:135], v[62:63]
	v_pk_fma_f32 v[60:61], v[68:69], v[132:133], v[60:61]
	v_pk_fma_f32 v[70:71], v[92:93], v[130:131], v[86:87]
	v_pk_fma_f32 v[68:69], v[94:95], v[128:129], v[84:85]
	global_store_dwordx4 v[74:75], v[60:63], off nt
	global_store_dwordx4 v[74:75], v[68:71], off offset:16 nt
	global_load_dwordx4 v[84:87], v[100:101], off
	s_nop 0
	global_load_dwordx4 v[68:71], v[154:155], off offset:512
	global_load_dwordx4 v[60:63], v[154:155], off offset:528
	v_pk_add_f32 v[94:95], v[56:57], 0 op_sel_hi:[1,0]
	v_lshl_add_u64 v[56:57], v[122:123], 0, v[78:79]
	v_pk_add_f32 v[92:93], v[58:59], 0 op_sel_hi:[1,0]
	v_lshl_add_u64 v[100:101], v[56:57], 1, s[8:9]
	s_waitcnt vmcnt(2)
	v_lshlrev_b32_e32 v56, 16, v84
	v_and_b32_e32 v57, 0xffff0000, v84
	v_lshlrev_b32_e32 v58, 16, v85
	v_and_b32_e32 v59, 0xffff0000, v85
	v_lshlrev_b32_e32 v84, 16, v86
	v_and_b32_e32 v85, 0xffff0000, v86
	v_lshlrev_b32_e32 v86, 16, v87
	v_and_b32_e32 v87, 0xffff0000, v87
	s_waitcnt vmcnt(1)
;     __device__ __forceinline__ void operator()(const f32x4 (&acc)[2][2][4][2], const Unit& u, int wr, int wc, int fr, int fq) const {
;     ...
;         for (int bj = 0; bj < 2; ++bj) { const int c = col0 + bj * HALF;
;             const f32x4 g0 = *(const f32x4*)(gp + c), g1 = *(const f32x4*)(gp + c + 4);
;             const f32x4 b0 = bias ? *(const f32x4*)(bias + c) : (f32x4){0.f, 0.f, 0.f, 0.f}, b1 = bias ? *(const f32x4*)(bias + c + 4) : (f32x4){0.f, 0.f, 0.f, 0.f};
; #pragma unroll
;             for (int ai = 0; ai < 2; ++ai)
; #pragma unroll
;                 for (int m = 0; m < 4; ++m) { const size_t off = (size_t)(row0 + ai * HALF + m * 16) * 1024 + c;
;                     f32x4 x0, x1;
;                     if (BASE_BF16) { const u32x4 v = *(const u32x4*)((const bf16_t*)base + off);
;                         x0 = (f32x4){__uint_as_float(v.x << 16), __uint_as_float(v.x & 0xffff0000u), __uint_as_float(v.y << 16), __uint_as_float(v.y & 0xffff0000u)};
;                         x1 = (f32x4){__uint_as_float(v.z << 16), __uint_as_float(v.z & 0xffff0000u), __uint_as_float(v.w << 16), __uint_as_float(v.w & 0xffff0000u)}; }
;                     else { x0 = *(const f32x4*)((const float*)base + off); x1 = *(const f32x4*)((const float*)base + off + 4); }
;                     x0 = x0 + g0 * (acc[ai][bj][m][0] + b0); x1 = x1 + g1 * (acc[ai][bj][m][1] + b1);
;                     if (OUT_BF16) { u32x4 w; w.x = pk2(x0[0], x0[1]); w.y = pk2(x0[2], x0[3]); w.z = pk2(x1[0], x1[1]); w.w = pk2(x1[2], x1[3]); *(u32x4*)((bf16_t*)out + off) = w; }
;                     else { *(f32x4*)((float*)out + off) = x0; *(f32x4*)((float*)out + off + 4) = x1; } } }
; template <class Epi, class Sched, bool ALIGN_EPI = false, bool SP2 = false>
; __device__ __forceinline__ void gemm_phase(PG8_LAS unsigned char* lds, const Gemm g, const Sched& S, const Epi& E) {
;     ...
;         if constexpr (ALIGN_EPI) { if (wr == 0) PG8_BAR; }
;         if constexpr (!Epi::AFTER_DRAIN) { E(acc, cur, wr, wc, fr, fq); S.done(cur); }
;         if (!has_next) break;
; #pragma unroll
;         for (int a = 0; a < 2; ++a)
; #pragma unroll
;             for (int b = 0; b < 2; ++b)
; #pragma unroll
;                 for (int m = 0; m < 4; ++m)
; #pragma unroll
;                     for (int n = 0; n < 2; ++n) acc[a][b][m][n] = (f32x4){0.f, 0.f, 0.f, 0.f};
;         cur = nxt; cA = nA; cB = nB; ++ui;
	v_pk_fma_f32 v[58:59], v[66:67], v[70:71], v[58:59]
	v_pk_fma_f32 v[56:57], v[64:65], v[68:69], v[56:57]
	s_waitcnt vmcnt(0)
	v_pk_fma_f32 v[66:67], v[92:93], v[62:63], v[86:87]
	v_pk_fma_f32 v[64:65], v[94:95], v[60:61], v[84:85]
	global_store_dwordx4 v[120:121], v[56:59], off offset:512 nt
	global_store_dwordx4 v[120:121], v[64:67], off offset:528 nt
	global_load_dwordx4 v[56:59], v[100:101], off
	s_nop 0
	v_pk_add_f32 v[66:67], v[48:49], 0 op_sel_hi:[1,0]
	v_lshl_add_u64 v[48:49], v[114:115], 0, v[78:79]
	v_pk_add_f32 v[64:65], v[50:51], 0 op_sel_hi:[1,0]
	v_lshl_add_u64 v[84:85], v[48:49], 1, s[8:9]
	s_waitcnt vmcnt(0)
	v_lshlrev_b32_e32 v48, 16, v56
	v_and_b32_e32 v49, 0xffff0000, v56
	v_lshlrev_b32_e32 v50, 16, v57
	v_and_b32_e32 v51, 0xffff0000, v57
	v_lshlrev_b32_e32 v56, 16, v58
	v_and_b32_e32 v57, 0xffff0000, v58
	v_lshlrev_b32_e32 v58, 16, v59
	v_and_b32_e32 v59, 0xffff0000, v59
	v_pk_fma_f32 v[50:51], v[54:55], v[70:71], v[50:51]
	v_pk_fma_f32 v[48:49], v[52:53], v[68:69], v[48:49]
	v_pk_fma_f32 v[54:55], v[64:65], v[62:63], v[58:59]
	v_pk_fma_f32 v[52:53], v[66:67], v[60:61], v[56:57]
	global_store_dwordx4 v[112:113], v[48:51], off offset:512 nt
	global_store_dwordx4 v[112:113], v[52:55], off offset:528 nt
	global_load_dwordx4 v[48:51], v[84:85], off
	s_nop 0
	v_pk_add_f32 v[54:55], v[40:41], 0 op_sel_hi:[1,0]
	v_lshl_add_u64 v[40:41], v[106:107], 0, v[78:79]
	v_pk_add_f32 v[52:53], v[42:43], 0 op_sel_hi:[1,0]
	v_lshl_add_u64 v[56:57], v[40:41], 1, s[8:9]
	s_waitcnt vmcnt(0)
	v_lshlrev_b32_e32 v40, 16, v48
	v_and_b32_e32 v41, 0xffff0000, v48
	v_lshlrev_b32_e32 v42, 16, v49
	v_and_b32_e32 v43, 0xffff0000, v49
	v_lshlrev_b32_e32 v48, 16, v50
	v_and_b32_e32 v49, 0xffff0000, v50
	v_lshlrev_b32_e32 v50, 16, v51
	v_and_b32_e32 v51, 0xffff0000, v51
	v_pk_fma_f32 v[42:43], v[46:47], v[70:71], v[42:43]
	v_pk_fma_f32 v[40:41], v[44:45], v[68:69], v[40:41]
	v_pk_fma_f32 v[46:47], v[52:53], v[62:63], v[50:51]
	v_pk_fma_f32 v[44:45], v[54:55], v[60:61], v[48:49]
	global_store_dwordx4 v[104:105], v[40:43], off offset:512 nt
	global_store_dwordx4 v[104:105], v[44:47], off offset:528 nt
	global_load_dwordx4 v[40:43], v[56:57], off
	s_nop 0
	v_pk_add_f32 v[46:47], v[32:33], 0 op_sel_hi:[1,0]
	v_lshl_add_u64 v[32:33], v[96:97], 0, v[78:79]
	v_pk_add_f32 v[44:45], v[34:35], 0 op_sel_hi:[1,0]
	v_lshl_add_u64 v[48:49], v[32:33], 1, s[8:9]
	s_waitcnt vmcnt(0)
	v_lshlrev_b32_e32 v32, 16, v40
	v_and_b32_e32 v33, 0xffff0000, v40
	v_lshlrev_b32_e32 v34, 16, v41
	v_and_b32_e32 v35, 0xffff0000, v41
	v_lshlrev_b32_e32 v40, 16, v42
	v_and_b32_e32 v41, 0xffff0000, v42
	v_lshlrev_b32_e32 v42, 16, v43
	v_and_b32_e32 v43, 0xffff0000, v43
	v_pk_fma_f32 v[34:35], v[38:39], v[70:71], v[34:35]
	v_pk_fma_f32 v[32:33], v[36:37], v[68:69], v[32:33]
	v_pk_fma_f32 v[38:39], v[44:45], v[62:63], v[42:43]
	v_pk_fma_f32 v[36:37], v[46:47], v[60:61], v[40:41]
	global_store_dwordx4 v[98:99], v[32:35], off offset:512 nt
	global_store_dwordx4 v[98:99], v[36:39], off offset:528 nt
	global_load_dwordx4 v[32:35], v[48:49], off
	s_nop 0
	v_pk_add_f32 v[38:39], v[24:25], 0 op_sel_hi:[1,0]
	v_lshl_add_u64 v[24:25], v[90:91], 0, v[78:79]
	v_pk_add_f32 v[36:37], v[26:27], 0 op_sel_hi:[1,0]
	v_lshl_add_u64 v[40:41], v[24:25], 1, s[8:9]
	s_waitcnt vmcnt(0)
	v_lshlrev_b32_e32 v24, 16, v32
	v_and_b32_e32 v25, 0xffff0000, v32
	v_lshlrev_b32_e32 v26, 16, v33
	v_and_b32_e32 v27, 0xffff0000, v33
	v_lshlrev_b32_e32 v32, 16, v34
	v_and_b32_e32 v33, 0xffff0000, v34
	v_lshlrev_b32_e32 v34, 16, v35
	v_and_b32_e32 v35, 0xffff0000, v35
	v_pk_fma_f32 v[26:27], v[30:31], v[70:71], v[26:27]
	v_pk_fma_f32 v[24:25], v[28:29], v[68:69], v[24:25]
	v_pk_fma_f32 v[30:31], v[36:37], v[62:63], v[34:35]
	v_pk_fma_f32 v[28:29], v[38:39], v[60:61], v[32:33]
	global_store_dwordx4 v[88:89], v[24:27], off offset:512 nt
	global_store_dwordx4 v[88:89], v[28:31], off offset:528 nt
	global_load_dwordx4 v[24:27], v[40:41], off
	s_nop 0
	v_pk_add_f32 v[30:31], v[16:17], 0 op_sel_hi:[1,0]
	v_lshl_add_u64 v[16:17], v[82:83], 0, v[78:79]
	v_pk_add_f32 v[28:29], v[18:19], 0 op_sel_hi:[1,0]
	v_lshl_add_u64 v[32:33], v[16:17], 1, s[8:9]
	s_waitcnt vmcnt(0)
	v_lshlrev_b32_e32 v16, 16, v24
	v_and_b32_e32 v17, 0xffff0000, v24
	v_lshlrev_b32_e32 v18, 16, v25
	v_and_b32_e32 v19, 0xffff0000, v25
	v_lshlrev_b32_e32 v24, 16, v26
	v_and_b32_e32 v25, 0xffff0000, v26
	v_lshlrev_b32_e32 v26, 16, v27
	v_and_b32_e32 v27, 0xffff0000, v27
	v_pk_fma_f32 v[18:19], v[22:23], v[70:71], v[18:19]
	v_pk_fma_f32 v[16:17], v[20:21], v[68:69], v[16:17]
	v_pk_fma_f32 v[22:23], v[28:29], v[62:63], v[26:27]
	v_pk_fma_f32 v[20:21], v[30:31], v[60:61], v[24:25]
	global_store_dwordx4 v[80:81], v[16:19], off offset:512 nt
	global_store_dwordx4 v[80:81], v[20:23], off offset:528 nt
	global_load_dwordx4 v[16:19], v[32:33], off
	s_nop 0
	v_pk_add_f32 v[22:23], v[8:9], 0 op_sel_hi:[1,0]
	v_lshl_add_u64 v[8:9], v[76:77], 0, v[78:79]
	v_pk_add_f32 v[20:21], v[10:11], 0 op_sel_hi:[1,0]
	v_lshl_add_u64 v[24:25], v[8:9], 1, s[8:9]
	s_waitcnt vmcnt(0)
	v_lshlrev_b32_e32 v8, 16, v16
	v_and_b32_e32 v9, 0xffff0000, v16
	v_lshlrev_b32_e32 v10, 16, v17
	v_and_b32_e32 v11, 0xffff0000, v17
	v_lshlrev_b32_e32 v16, 16, v18
	v_and_b32_e32 v17, 0xffff0000, v18
	v_lshlrev_b32_e32 v18, 16, v19
	v_and_b32_e32 v19, 0xffff0000, v19
	v_pk_fma_f32 v[10:11], v[14:15], v[70:71], v[10:11]
	v_pk_fma_f32 v[8:9], v[12:13], v[68:69], v[8:9]
	v_pk_fma_f32 v[14:15], v[20:21], v[62:63], v[18:19]
	v_pk_fma_f32 v[12:13], v[22:23], v[60:61], v[16:17]
	global_store_dwordx4 v[72:73], v[8:11], off offset:512 nt
	global_store_dwordx4 v[72:73], v[12:15], off offset:528 nt
	global_load_dwordx4 v[8:11], v[24:25], off
	s_nop 0
	v_pk_add_f32 v[12:13], v[2:3], 0 op_sel_hi:[1,0]
	v_pk_add_f32 v[14:15], v[0:1], 0 op_sel_hi:[1,0]
	s_waitcnt vmcnt(0)
	v_lshlrev_b32_e32 v0, 16, v8
	v_and_b32_e32 v1, 0xffff0000, v8
	v_lshlrev_b32_e32 v2, 16, v9
	v_and_b32_e32 v3, 0xffff0000, v9
	v_lshlrev_b32_e32 v8, 16, v10
	v_and_b32_e32 v9, 0xffff0000, v10
	v_lshlrev_b32_e32 v10, 16, v11
	v_and_b32_e32 v11, 0xffff0000, v11
	v_pk_fma_f32 v[2:3], v[6:7], v[70:71], v[2:3]
	v_pk_fma_f32 v[0:1], v[4:5], v[68:69], v[0:1]
	v_pk_fma_f32 v[6:7], v[12:13], v[62:63], v[10:11]
	v_pk_fma_f32 v[4:5], v[14:15], v[60:61], v[8:9]
	global_store_dwordx4 v[74:75], v[0:3], off offset:512 nt
	global_store_dwordx4 v[74:75], v[4:7], off offset:528 nt
	s_cbranch_vccnz .LBB0_1405
	s_andn2_b64 vcc, exec, s[6:7]
	s_cbranch_vccnz .LBB0_1404
	s_barrier
	s_branch .LBB0_1404
